# EpiResGate (P4 and P6 epilogues) rewritten: all gate/scale/xin loads pipelined 8 deep with counted vmcnt; attention waves 4-7 issue all K/V LDS-DMA
# baseline (speedup 1.0000x reference)
;     __device__ __forceinline__ void operator()(const f32x4 (&acc)[2][2][4][2], const Unit& u, int wr_, int wc_, int fr_, int fq_) const {
;         int tx = threadIdx.x; asm volatile("" : "+v"(tx));
;         const int fr = tx & 15, fq = (tx >> 4) & 3, wc = (tx >> 6) & 3, wr = tx >> 8;
;         const int b = u.pm >> 5;
;         const int col0 = u.pn * BM + wc * 32 + 8 * fq;
;         const float* gp = gate + (size_t)b * 6144 + col0;
;         f32x4 gv[2][2], sv[2][2];
; #pragma unroll
;         for (int bj = 0; bj < 2; ++bj)
; #pragma unroll
;             for (int n = 0; n < 2; ++n) { gv[bj][n] = *(const f32x4*)(gp + bj * HALF + n * 4);
;                 sv[bj][n] = anext ? *(const f32x4*)(scale_next + (size_t)b * 6144 + col0 + bj * HALF + n * 4) + 1.0f : (f32x4){0.f, 0.f, 0.f, 0.f}; }
.LBB0_948:
	s_and_b64 vcc, exec, s[82:83]
	s_cbranch_vccnz .Lrg4_fast
	s_branch .Lrg4_fastn

; __device__ __forceinline__ unsigned cvt_pk_bf16(float lo, float hi) { unsigned r; asm volatile("v_cvt_pk_bf16_f32 %0, %1, %2" : "=v"(r) : "v"(lo), "v"(hi)); return r; }
;     __device__ __forceinline__ void operator()(const f32x4 (&acc)[2][2][4][2], const Unit& u, int wr_, int wc_, int fr_, int fq_) const {
;     ...
;         const int b = u.pm >> 5;
;         const int col0 = u.pn * BM + wc * 32 + 8 * fq;
;         const float* gp = gate + (size_t)b * 6144 + col0;
;         f32x4 gv[2][2], sv[2][2];
; #pragma unroll
;         for (int bj = 0; bj < 2; ++bj)
; #pragma unroll
;             for (int n = 0; n < 2; ++n) { gv[bj][n] = *(const f32x4*)(gp + bj * HALF + n * 4);
;                 sv[bj][n] = anext ? *(const f32x4*)(scale_next + (size_t)b * 6144 + col0 + bj * HALF + n * 4) + 1.0f : (f32x4){0.f, 0.f, 0.f, 0.f}; }
; #pragma unroll
;         for (int ai = 0; ai < 2; ++ai)
; #pragma unroll
;             for (int m = 0; m < 4; ++m) { int row = u.pm * BM + ai * HALF + wr * 64 + m * 16 + fr; asm volatile("" : "+v"(row));
;                 const size_t off = (size_t)row * 1024 + col0; float ss = 0.f;
; #pragma unroll
;                 for (int bj = 0; bj < 2; ++bj) { u32x4 w;
; #pragma unroll
;                     for (int n = 0; n < 2; ++n) { const f32x4 xi = *(const f32x4*)(xin + off + bj * HALF + n * 4);
;                         const f32x4 xn = xi + gv[bj][n] * acc[ai][bj][m][n];
;                         *(f32x4*)(xout + off + bj * HALF + n * 4) = xn;
;                         if (anext) { ss += (xn[0] * xn[0] + xn[1] * xn[1]) + (xn[2] * xn[2] + xn[3] * xn[3]);
;                             const f32x4 an = xn * sv[bj][n]; w[2 * n] = cvt_pk_bf16(an[0], an[1]); w[2 * n + 1] = cvt_pk_bf16(an[2], an[3]); } }
;                     if (anext) *(u32x4*)(anext + off + bj * HALF) = w; }
;                 if (anext) { ss += __shfl_xor(ss, 16); ss += __shfl_xor(ss, 32); if (fq == 0) atomicAdd(rss_next + row, ss); }
.Lrg4_fast:
	s_movk_i32 s49, 0x4000
	s_mov_b32 s51, 0x10000
	s_mov_b32 s52, 0x14000
	v_bfe_u32 v227, v190, 4, 2
	v_lshrrev_b32_e32 v144, 1, v190
	v_and_b32_e32 v144, 0x60, v144
	s_lshl_b32 s6, s43, 8
	v_lshlrev_b32_e32 v145, 3, v227
	v_or3_b32 v180, v144, s6, v145
	v_lshlrev_b32_e32 v181, 2, v180
	s_ashr_i32 s6, s33, 5
	s_mul_i32 s6, s6, 0x6000
	s_add_u32 s4, s35, s6
	s_addc_u32 s5, s36, 0
	global_load_dwordx4 v[56:59], v181, s[4:5]
	global_load_dwordx4 v[52:55], v181, s[4:5] offset:16
	global_load_dwordx4 v[40:43], v181, s[4:5] offset:512
	global_load_dwordx4 v[44:47], v181, s[4:5] offset:528
	s_add_u32 s22, s37, s6
	s_addc_u32 s23, s40, 0
	global_load_dwordx4 v[176:179], v181, s[22:23]
	global_load_dwordx4 v[172:175], v181, s[22:23] offset:16
	global_load_dwordx4 v[168:171], v181, s[22:23] offset:512
	global_load_dwordx4 v[164:167], v181, s[22:23] offset:528
	s_lshl_b32 s6, s33, 8
	v_ashrrev_i32_e32 v144, 2, v190
	v_and_b32_e32 v144, 0xffffffc0, v144
	v_and_or_b32 v145, v190, 15, s6
	v_add_u32_e32 v184, v145, v144
	v_lshl_add_u32 v182, v184, 10, v180
	v_lshlrev_b32_e32 v183, 1, v182
	v_lshlrev_b32_e32 v182, 2, v182
	v_lshlrev_b32_e32 v184, 2, v184
	v_mbcnt_lo_u32_b32 v226, -1, 0
	v_mbcnt_hi_u32_b32 v226, -1, v226
	v_xor_b32_e32 v185, 16, v226
	v_lshlrev_b32_e32 v185, 2, v185
	v_xor_b32_e32 v186, 32, v226
	v_lshlrev_b32_e32 v186, 2, v186
	v_cmp_eq_u32_e64 s[6:7], 0, v227
	global_load_dwordx4 v[228:231], v182, s[10:11]
	global_load_dwordx4 v[232:235], v182, s[10:11] offset:16
	global_load_dwordx4 v[236:239], v182, s[10:11] offset:512
	global_load_dwordx4 v[240:243], v182, s[10:11] offset:528
	s_add_u32 s4, s10, 0x10000
	s_addc_u32 s5, s11, 0
	global_load_dwordx4 v[244:247], v182, s[4:5]
	s_add_u32 s4, s10, 0x10000
	s_addc_u32 s5, s11, 0
	global_load_dwordx4 v[248:251], v182, s[4:5] offset:16
	s_add_u32 s4, s10, 0x10000
	s_addc_u32 s5, s11, 0
	global_load_dwordx4 v[208:211], v182, s[4:5] offset:512
	s_add_u32 s4, s10, 0x10000
	s_addc_u32 s5, s11, 0
	global_load_dwordx4 v[212:215], v182, s[4:5] offset:528
	s_waitcnt vmcnt(8)
	v_pk_add_f32 v[176:177], v[176:177], 1.0 op_sel_hi:[1,0]
	v_pk_add_f32 v[178:179], v[178:179], 1.0 op_sel_hi:[1,0]
	v_pk_add_f32 v[172:173], v[172:173], 1.0 op_sel_hi:[1,0]
	v_pk_add_f32 v[174:175], v[174:175], 1.0 op_sel_hi:[1,0]
	v_pk_add_f32 v[168:169], v[168:169], 1.0 op_sel_hi:[1,0]
	v_pk_add_f32 v[170:171], v[170:171], 1.0 op_sel_hi:[1,0]
	v_pk_add_f32 v[164:165], v[164:165], 1.0 op_sel_hi:[1,0]
	v_pk_add_f32 v[166:167], v[166:167], 1.0 op_sel_hi:[1,0]
	s_waitcnt vmcnt(7)
	v_pk_fma_f32 v[140:141], v[140:141], v[56:57], v[228:229]
	v_pk_fma_f32 v[142:143], v[142:143], v[58:59], v[230:231]
	global_store_dwordx4 v182, v[140:143], s[88:89]
	s_add_u32 s4, s10, 0x20000
	s_addc_u32 s5, s11, 0
	global_load_dwordx4 v[228:231], v182, s[4:5]
	v_pk_mul_f32 v[144:145], v[140:141], v[140:141]
	v_pk_mul_f32 v[146:147], v[142:143], v[142:143]
	v_pk_mul_f32 v[220:221], v[176:177], v[140:141]
	v_pk_mul_f32 v[222:223], v[178:179], v[142:143]
	v_add_f32_e32 v144, v144, v145
	v_add_f32_e32 v146, v146, v147
	v_cvt_pk_bf16_f32 v216, v220, v221
	v_cvt_pk_bf16_f32 v217, v222, v223
	v_add_f32_e32 v187, v144, v146
	s_waitcnt vmcnt(8)
	v_pk_fma_f32 v[136:137], v[136:137], v[52:53], v[232:233]
	v_pk_fma_f32 v[138:139], v[138:139], v[54:55], v[234:235]
	global_store_dwordx4 v182, v[136:139], s[88:89] offset:16
	s_add_u32 s4, s10, 0x20000
	s_addc_u32 s5, s11, 0
	global_load_dwordx4 v[232:235], v182, s[4:5] offset:16
	v_pk_mul_f32 v[144:145], v[136:137], v[136:137]
	v_pk_mul_f32 v[146:147], v[138:139], v[138:139]
	v_pk_mul_f32 v[220:221], v[172:173], v[136:137]
	v_pk_mul_f32 v[222:223], v[174:175], v[138:139]
	v_add_f32_e32 v144, v144, v145
	v_add_f32_e32 v146, v146, v147
	v_cvt_pk_bf16_f32 v218, v220, v221
	v_cvt_pk_bf16_f32 v219, v222, v223
	v_add_f32_e32 v144, v144, v146
	v_add_f32_e32 v187, v187, v144
	global_store_dwordx4 v183, v[216:219], s[56:57]
	s_waitcnt vmcnt(10)
	v_pk_fma_f32 v[132:133], v[132:133], v[40:41], v[236:237]
	v_pk_fma_f32 v[134:135], v[134:135], v[42:43], v[238:239]
	global_store_dwordx4 v182, v[132:135], s[88:89] offset:512
	s_add_u32 s4, s10, 0x20000
	s_addc_u32 s5, s11, 0
	global_load_dwordx4 v[236:239], v182, s[4:5] offset:512
	v_pk_mul_f32 v[144:145], v[132:133], v[132:133]
	v_pk_mul_f32 v[146:147], v[134:135], v[134:135]
	v_pk_mul_f32 v[220:221], v[168:169], v[132:133]
	v_pk_mul_f32 v[222:223], v[170:171], v[134:135]
	v_add_f32_e32 v144, v144, v145
	v_add_f32_e32 v146, v146, v147
	v_cvt_pk_bf16_f32 v194, v220, v221
	v_cvt_pk_bf16_f32 v195, v222, v223
	v_add_f32_e32 v144, v144, v146
	v_add_f32_e32 v187, v187, v144
	s_waitcnt vmcnt(11)
	v_pk_fma_f32 v[128:129], v[128:129], v[44:45], v[240:241]
	v_pk_fma_f32 v[130:131], v[130:131], v[46:47], v[242:243]
	global_store_dwordx4 v182, v[128:131], s[88:89] offset:528
	s_add_u32 s4, s10, 0x20000
	s_addc_u32 s5, s11, 0
	global_load_dwordx4 v[240:243], v182, s[4:5] offset:528
	v_pk_mul_f32 v[144:145], v[128:129], v[128:129]
	v_pk_mul_f32 v[146:147], v[130:131], v[130:131]
	v_pk_mul_f32 v[220:221], v[164:165], v[128:129]
	v_pk_mul_f32 v[222:223], v[166:167], v[130:131]
	v_add_f32_e32 v144, v144, v145
	v_add_f32_e32 v146, v146, v147
	v_cvt_pk_bf16_f32 v196, v220, v221
	v_cvt_pk_bf16_f32 v197, v222, v223
	v_add_f32_e32 v144, v144, v146
	v_add_f32_e32 v187, v187, v144
	global_store_dwordx4 v183, v[194:197], s[56:57] offset:256
	ds_bpermute_b32 v225, v185, v187
	s_waitcnt vmcnt(13)
; __device__ __forceinline__ unsigned cvt_pk_bf16(float lo, float hi) { unsigned r; asm volatile("v_cvt_pk_bf16_f32 %0, %1, %2" : "=v"(r) : "v"(lo), "v"(hi)); return r; }
;     __device__ __forceinline__ void operator()(const f32x4 (&acc)[2][2][4][2], const Unit& u, int wr_, int wc_, int fr_, int fq_) const {
;     ...
;             for (int m = 0; m < 4; ++m) { int row = u.pm * BM + ai * HALF + wr * 64 + m * 16 + fr; asm volatile("" : "+v"(row));
;                 const size_t off = (size_t)row * 1024 + col0; float ss = 0.f;
; #pragma unroll
;                 for (int bj = 0; bj < 2; ++bj) { u32x4 w;
; #pragma unroll
;                     for (int n = 0; n < 2; ++n) { const f32x4 xi = *(const f32x4*)(xin + off + bj * HALF + n * 4);
;                         const f32x4 xn = xi + gv[bj][n] * acc[ai][bj][m][n];
;                         *(f32x4*)(xout + off + bj * HALF + n * 4) = xn;
;                         if (anext) { ss += (xn[0] * xn[0] + xn[1] * xn[1]) + (xn[2] * xn[2] + xn[3] * xn[3]);
;                             const f32x4 an = xn * sv[bj][n]; w[2 * n] = cvt_pk_bf16(an[0], an[1]); w[2 * n + 1] = cvt_pk_bf16(an[2], an[3]); } }
;                     if (anext) *(u32x4*)(anext + off + bj * HALF) = w; }
;                 if (anext) { ss += __shfl_xor(ss, 16); ss += __shfl_xor(ss, 32); if (fq == 0) atomicAdd(rss_next + row, ss); }
;                 asm volatile("" ::: "memory"); }
	v_pk_fma_f32 v[124:125], v[124:125], v[56:57], v[244:245]
	v_pk_fma_f32 v[126:127], v[126:127], v[58:59], v[246:247]
	s_add_u32 s22, s88, 0x10000
	s_addc_u32 s23, s89, 0
	global_store_dwordx4 v182, v[124:127], s[22:23]
	s_add_u32 s4, s10, 0x30000
	s_addc_u32 s5, s11, 0
	global_load_dwordx4 v[244:247], v182, s[4:5]
	v_pk_mul_f32 v[144:145], v[124:125], v[124:125]
	v_pk_mul_f32 v[146:147], v[126:127], v[126:127]
	v_pk_mul_f32 v[220:221], v[176:177], v[124:125]
	v_pk_mul_f32 v[222:223], v[178:179], v[126:127]
	v_add_f32_e32 v144, v144, v145
	v_add_f32_e32 v146, v146, v147
	v_cvt_pk_bf16_f32 v216, v220, v221
	v_cvt_pk_bf16_f32 v217, v222, v223
	v_add_f32_e32 v224, v144, v146
	s_waitcnt vmcnt(14)
	v_pk_fma_f32 v[120:121], v[120:121], v[52:53], v[248:249]
	v_pk_fma_f32 v[122:123], v[122:123], v[54:55], v[250:251]
	s_add_u32 s22, s88, 0x10000
	s_addc_u32 s23, s89, 0
	global_store_dwordx4 v182, v[120:123], s[22:23] offset:16
	s_add_u32 s4, s10, 0x30000
	s_addc_u32 s5, s11, 0
	global_load_dwordx4 v[248:251], v182, s[4:5] offset:16
	v_pk_mul_f32 v[144:145], v[120:121], v[120:121]
	v_pk_mul_f32 v[146:147], v[122:123], v[122:123]
	v_pk_mul_f32 v[220:221], v[172:173], v[120:121]
	v_pk_mul_f32 v[222:223], v[174:175], v[122:123]
	v_add_f32_e32 v144, v144, v145
	v_add_f32_e32 v146, v146, v147
	v_cvt_pk_bf16_f32 v218, v220, v221
	v_cvt_pk_bf16_f32 v219, v222, v223
	v_add_f32_e32 v144, v144, v146
	v_add_f32_e32 v224, v224, v144
	s_add_u32 s22, s56, 0x8000
	s_addc_u32 s23, s57, 0
	global_store_dwordx4 v183, v[216:219], s[22:23]
	s_waitcnt lgkmcnt(0)
	v_add_f32_e32 v187, v187, v225
	ds_bpermute_b32 v225, v186, v187
	s_waitcnt vmcnt(16)
	v_pk_fma_f32 v[116:117], v[116:117], v[40:41], v[208:209]
	v_pk_fma_f32 v[118:119], v[118:119], v[42:43], v[210:211]
	s_add_u32 s22, s88, 0x10000
	s_addc_u32 s23, s89, 0
	global_store_dwordx4 v182, v[116:119], s[22:23] offset:512
	s_add_u32 s4, s10, 0x30000
	s_addc_u32 s5, s11, 0
	global_load_dwordx4 v[208:211], v182, s[4:5] offset:512
	v_pk_mul_f32 v[144:145], v[116:117], v[116:117]
	v_pk_mul_f32 v[146:147], v[118:119], v[118:119]
	v_pk_mul_f32 v[220:221], v[168:169], v[116:117]
	v_pk_mul_f32 v[222:223], v[170:171], v[118:119]
	v_add_f32_e32 v144, v144, v145
	v_add_f32_e32 v146, v146, v147
	v_cvt_pk_bf16_f32 v194, v220, v221
	v_cvt_pk_bf16_f32 v195, v222, v223
	v_add_f32_e32 v144, v144, v146
	v_add_f32_e32 v224, v224, v144
	s_waitcnt lgkmcnt(0)
	v_add_f32_e32 v225, v187, v225
	s_and_saveexec_b64 vcc, s[6:7]
	global_atomic_add_f32 v184, v225, s[8:9]
	s_mov_b64 exec, vcc
	s_waitcnt vmcnt(18)
	v_pk_fma_f32 v[112:113], v[112:113], v[44:45], v[212:213]
	v_pk_fma_f32 v[114:115], v[114:115], v[46:47], v[214:215]
	s_add_u32 s22, s88, 0x10000
	s_addc_u32 s23, s89, 0
	global_store_dwordx4 v182, v[112:115], s[22:23] offset:528
	s_add_u32 s4, s10, 0x30000
	s_addc_u32 s5, s11, 0
	global_load_dwordx4 v[212:215], v182, s[4:5] offset:528
	v_pk_mul_f32 v[144:145], v[112:113], v[112:113]
	v_pk_mul_f32 v[146:147], v[114:115], v[114:115]
	v_pk_mul_f32 v[220:221], v[164:165], v[112:113]
	v_pk_mul_f32 v[222:223], v[166:167], v[114:115]
	v_add_f32_e32 v144, v144, v145
	v_add_f32_e32 v146, v146, v147
	v_cvt_pk_bf16_f32 v196, v220, v221
	v_cvt_pk_bf16_f32 v197, v222, v223
	v_add_f32_e32 v144, v144, v146
	v_add_f32_e32 v224, v224, v144
	s_add_u32 s22, s56, 0x8000
	s_addc_u32 s23, s57, 0
	global_store_dwordx4 v183, v[194:197], s[22:23] offset:256
	ds_bpermute_b32 v225, v185, v224
	s_waitcnt vmcnt(19)
	v_pk_fma_f32 v[108:109], v[108:109], v[56:57], v[228:229]
	v_pk_fma_f32 v[110:111], v[110:111], v[58:59], v[230:231]
	s_add_u32 s22, s88, 0x20000
	s_addc_u32 s23, s89, 0
	global_store_dwordx4 v182, v[108:111], s[22:23]
	s_add_u32 s4, s10, 0x80000
	s_addc_u32 s5, s11, 0
	global_load_dwordx4 v[228:231], v182, s[4:5]
	v_pk_mul_f32 v[144:145], v[108:109], v[108:109]
	v_pk_mul_f32 v[146:147], v[110:111], v[110:111]
	v_pk_mul_f32 v[220:221], v[176:177], v[108:109]
	v_pk_mul_f32 v[222:223], v[178:179], v[110:111]
	v_add_f32_e32 v144, v144, v145
	v_add_f32_e32 v146, v146, v147
	v_cvt_pk_bf16_f32 v216, v220, v221
	v_cvt_pk_bf16_f32 v217, v222, v223
	v_add_f32_e32 v187, v144, v146
	s_waitcnt vmcnt(19)
	v_pk_fma_f32 v[104:105], v[104:105], v[52:53], v[232:233]
	v_pk_fma_f32 v[106:107], v[106:107], v[54:55], v[234:235]
	s_add_u32 s22, s88, 0x20000
	s_addc_u32 s23, s89, 0
	global_store_dwordx4 v182, v[104:107], s[22:23] offset:16
	s_add_u32 s4, s10, 0x80000
	s_addc_u32 s5, s11, 0
	global_load_dwordx4 v[232:235], v182, s[4:5] offset:16
	v_pk_mul_f32 v[144:145], v[104:105], v[104:105]
	v_pk_mul_f32 v[146:147], v[106:107], v[106:107]
	v_pk_mul_f32 v[220:221], v[172:173], v[104:105]
	v_pk_mul_f32 v[222:223], v[174:175], v[106:107]
	v_add_f32_e32 v144, v144, v145
	v_add_f32_e32 v146, v146, v147
	v_cvt_pk_bf16_f32 v218, v220, v221
	v_cvt_pk_bf16_f32 v219, v222, v223
	v_add_f32_e32 v144, v144, v146
	v_add_f32_e32 v187, v187, v144
	s_add_u32 s22, s56, 0x10000
	s_addc_u32 s23, s57, 0
	global_store_dwordx4 v183, v[216:219], s[22:23]
	s_waitcnt lgkmcnt(0)
	v_add_f32_e32 v224, v224, v225
	ds_bpermute_b32 v225, v186, v224
	s_waitcnt vmcnt(19)
	v_pk_fma_f32 v[100:101], v[100:101], v[40:41], v[236:237]
	v_pk_fma_f32 v[102:103], v[102:103], v[42:43], v[238:239]
	s_add_u32 s22, s88, 0x20000
	s_addc_u32 s23, s89, 0
	global_store_dwordx4 v182, v[100:103], s[22:23] offset:512
	s_add_u32 s4, s10, 0x80000
	s_addc_u32 s5, s11, 0
	global_load_dwordx4 v[236:239], v182, s[4:5] offset:512
	v_pk_mul_f32 v[144:145], v[100:101], v[100:101]
	v_pk_mul_f32 v[146:147], v[102:103], v[102:103]
	v_pk_mul_f32 v[220:221], v[168:169], v[100:101]
	v_pk_mul_f32 v[222:223], v[170:171], v[102:103]
	v_add_f32_e32 v144, v144, v145
	v_add_f32_e32 v146, v146, v147
	v_cvt_pk_bf16_f32 v194, v220, v221
	v_cvt_pk_bf16_f32 v195, v222, v223
	v_add_f32_e32 v144, v144, v146
	v_add_f32_e32 v187, v187, v144
	s_waitcnt lgkmcnt(0)
; __device__ __forceinline__ unsigned cvt_pk_bf16(float lo, float hi) { unsigned r; asm volatile("v_cvt_pk_bf16_f32 %0, %1, %2" : "=v"(r) : "v"(lo), "v"(hi)); return r; }
;     __device__ __forceinline__ void operator()(const f32x4 (&acc)[2][2][4][2], const Unit& u, int wr_, int wc_, int fr_, int fq_) const {
;     ...
;             for (int m = 0; m < 4; ++m) { int row = u.pm * BM + ai * HALF + wr * 64 + m * 16 + fr; asm volatile("" : "+v"(row));
;                 const size_t off = (size_t)row * 1024 + col0; float ss = 0.f;
; #pragma unroll
;                 for (int bj = 0; bj < 2; ++bj) { u32x4 w;
; #pragma unroll
;                     for (int n = 0; n < 2; ++n) { const f32x4 xi = *(const f32x4*)(xin + off + bj * HALF + n * 4);
;                         const f32x4 xn = xi + gv[bj][n] * acc[ai][bj][m][n];
;                         *(f32x4*)(xout + off + bj * HALF + n * 4) = xn;
;                         if (anext) { ss += (xn[0] * xn[0] + xn[1] * xn[1]) + (xn[2] * xn[2] + xn[3] * xn[3]);
;                             const f32x4 an = xn * sv[bj][n]; w[2 * n] = cvt_pk_bf16(an[0], an[1]); w[2 * n + 1] = cvt_pk_bf16(an[2], an[3]); } }
;                     if (anext) *(u32x4*)(anext + off + bj * HALF) = w; }
;                 if (anext) { ss += __shfl_xor(ss, 16); ss += __shfl_xor(ss, 32); if (fq == 0) atomicAdd(rss_next + row, ss); }
;                 asm volatile("" ::: "memory"); }
	v_add_f32_e32 v225, v224, v225
	s_and_saveexec_b64 vcc, s[6:7]
	global_atomic_add_f32 v184, v225, s[8:9] offset:64
	s_mov_b64 exec, vcc
	s_waitcnt vmcnt(20)
	v_pk_fma_f32 v[96:97], v[96:97], v[44:45], v[240:241]
	v_pk_fma_f32 v[98:99], v[98:99], v[46:47], v[242:243]
	s_add_u32 s22, s88, 0x20000
	s_addc_u32 s23, s89, 0
	global_store_dwordx4 v182, v[96:99], s[22:23] offset:528
	s_add_u32 s4, s10, 0x80000
	s_addc_u32 s5, s11, 0
	global_load_dwordx4 v[240:243], v182, s[4:5] offset:528
	v_pk_mul_f32 v[144:145], v[96:97], v[96:97]
	v_pk_mul_f32 v[146:147], v[98:99], v[98:99]
	v_pk_mul_f32 v[220:221], v[164:165], v[96:97]
	v_pk_mul_f32 v[222:223], v[166:167], v[98:99]
	v_add_f32_e32 v144, v144, v145
	v_add_f32_e32 v146, v146, v147
	v_cvt_pk_bf16_f32 v196, v220, v221
	v_cvt_pk_bf16_f32 v197, v222, v223
	v_add_f32_e32 v144, v144, v146
	v_add_f32_e32 v187, v187, v144
	s_add_u32 s22, s56, 0x10000
	s_addc_u32 s23, s57, 0
	global_store_dwordx4 v183, v[194:197], s[22:23] offset:256
	ds_bpermute_b32 v225, v185, v187
	s_waitcnt vmcnt(20)
	v_pk_fma_f32 v[92:93], v[92:93], v[56:57], v[244:245]
	v_pk_fma_f32 v[94:95], v[94:95], v[58:59], v[246:247]
	s_add_u32 s22, s88, 0x30000
	s_addc_u32 s23, s89, 0
	global_store_dwordx4 v182, v[92:95], s[22:23]
	s_add_u32 s4, s10, 0x90000
	s_addc_u32 s5, s11, 0
	global_load_dwordx4 v[244:247], v182, s[4:5]
	v_pk_mul_f32 v[144:145], v[92:93], v[92:93]
	v_pk_mul_f32 v[146:147], v[94:95], v[94:95]
	v_pk_mul_f32 v[220:221], v[176:177], v[92:93]
	v_pk_mul_f32 v[222:223], v[178:179], v[94:95]
	v_add_f32_e32 v144, v144, v145
	v_add_f32_e32 v146, v146, v147
	v_cvt_pk_bf16_f32 v216, v220, v221
	v_cvt_pk_bf16_f32 v217, v222, v223
	v_add_f32_e32 v224, v144, v146
	s_waitcnt vmcnt(20)
	v_pk_fma_f32 v[88:89], v[88:89], v[52:53], v[248:249]
	v_pk_fma_f32 v[90:91], v[90:91], v[54:55], v[250:251]
	s_add_u32 s22, s88, 0x30000
	s_addc_u32 s23, s89, 0
	global_store_dwordx4 v182, v[88:91], s[22:23] offset:16
	s_add_u32 s4, s10, 0x90000
	s_addc_u32 s5, s11, 0
	global_load_dwordx4 v[248:251], v182, s[4:5] offset:16
	v_pk_mul_f32 v[144:145], v[88:89], v[88:89]
	v_pk_mul_f32 v[146:147], v[90:91], v[90:91]
	v_pk_mul_f32 v[220:221], v[172:173], v[88:89]
	v_pk_mul_f32 v[222:223], v[174:175], v[90:91]
	v_add_f32_e32 v144, v144, v145
	v_add_f32_e32 v146, v146, v147
	v_cvt_pk_bf16_f32 v218, v220, v221
	v_cvt_pk_bf16_f32 v219, v222, v223
	v_add_f32_e32 v144, v144, v146
	v_add_f32_e32 v224, v224, v144
	s_add_u32 s22, s56, 0x18000
	s_addc_u32 s23, s57, 0
	global_store_dwordx4 v183, v[216:219], s[22:23]
	s_waitcnt lgkmcnt(0)
	v_add_f32_e32 v187, v187, v225
	ds_bpermute_b32 v225, v186, v187
	s_waitcnt vmcnt(20)
	v_pk_fma_f32 v[84:85], v[84:85], v[40:41], v[208:209]
	v_pk_fma_f32 v[86:87], v[86:87], v[42:43], v[210:211]
	s_add_u32 s22, s88, 0x30000
	s_addc_u32 s23, s89, 0
	global_store_dwordx4 v182, v[84:87], s[22:23] offset:512
	s_add_u32 s4, s10, 0x90000
	s_addc_u32 s5, s11, 0
	global_load_dwordx4 v[208:211], v182, s[4:5] offset:512
	v_pk_mul_f32 v[144:145], v[84:85], v[84:85]
	v_pk_mul_f32 v[146:147], v[86:87], v[86:87]
	v_pk_mul_f32 v[220:221], v[168:169], v[84:85]
	v_pk_mul_f32 v[222:223], v[170:171], v[86:87]
	v_add_f32_e32 v144, v144, v145
	v_add_f32_e32 v146, v146, v147
	v_cvt_pk_bf16_f32 v194, v220, v221
	v_cvt_pk_bf16_f32 v195, v222, v223
	v_add_f32_e32 v144, v144, v146
	v_add_f32_e32 v224, v224, v144
	s_waitcnt lgkmcnt(0)
	v_add_f32_e32 v225, v187, v225
	s_and_saveexec_b64 vcc, s[6:7]
	global_atomic_add_f32 v184, v225, s[8:9] offset:128
	s_mov_b64 exec, vcc
	s_waitcnt vmcnt(20)
	v_pk_fma_f32 v[80:81], v[80:81], v[44:45], v[212:213]
	v_pk_fma_f32 v[82:83], v[82:83], v[46:47], v[214:215]
	s_add_u32 s22, s88, 0x30000
	s_addc_u32 s23, s89, 0
	global_store_dwordx4 v182, v[80:83], s[22:23] offset:528
	s_add_u32 s4, s10, 0x90000
	s_addc_u32 s5, s11, 0
	global_load_dwordx4 v[212:215], v182, s[4:5] offset:528
	v_pk_mul_f32 v[144:145], v[80:81], v[80:81]
	v_pk_mul_f32 v[146:147], v[82:83], v[82:83]
	v_pk_mul_f32 v[220:221], v[164:165], v[80:81]
	v_pk_mul_f32 v[222:223], v[166:167], v[82:83]
	v_add_f32_e32 v144, v144, v145
	v_add_f32_e32 v146, v146, v147
	v_cvt_pk_bf16_f32 v196, v220, v221
	v_cvt_pk_bf16_f32 v197, v222, v223
	v_add_f32_e32 v144, v144, v146
	v_add_f32_e32 v224, v224, v144
	s_add_u32 s22, s56, 0x18000
	s_addc_u32 s23, s57, 0
	global_store_dwordx4 v183, v[194:197], s[22:23] offset:256
	ds_bpermute_b32 v225, v185, v224
	s_waitcnt vmcnt(20)
	v_pk_fma_f32 v[76:77], v[76:77], v[56:57], v[228:229]
	v_pk_fma_f32 v[78:79], v[78:79], v[58:59], v[230:231]
	s_add_u32 s22, s88, 0x80000
	s_addc_u32 s23, s89, 0
	global_store_dwordx4 v182, v[76:79], s[22:23]
	s_add_u32 s4, s10, 0xa0000
	s_addc_u32 s5, s11, 0
	global_load_dwordx4 v[228:231], v182, s[4:5]
	v_pk_mul_f32 v[144:145], v[76:77], v[76:77]
	v_pk_mul_f32 v[146:147], v[78:79], v[78:79]
	v_pk_mul_f32 v[220:221], v[176:177], v[76:77]
	v_pk_mul_f32 v[222:223], v[178:179], v[78:79]
	v_add_f32_e32 v144, v144, v145
	v_add_f32_e32 v146, v146, v147
	v_cvt_pk_bf16_f32 v216, v220, v221
	v_cvt_pk_bf16_f32 v217, v222, v223
	v_add_f32_e32 v187, v144, v146
	s_waitcnt vmcnt(20)
	v_pk_fma_f32 v[72:73], v[72:73], v[52:53], v[232:233]
	v_pk_fma_f32 v[74:75], v[74:75], v[54:55], v[234:235]
	s_add_u32 s22, s88, 0x80000
	s_addc_u32 s23, s89, 0
	global_store_dwordx4 v182, v[72:75], s[22:23] offset:16
	s_add_u32 s4, s10, 0xa0000
	s_addc_u32 s5, s11, 0
	global_load_dwordx4 v[232:235], v182, s[4:5] offset:16
	v_pk_mul_f32 v[144:145], v[72:73], v[72:73]
	v_pk_mul_f32 v[146:147], v[74:75], v[74:75]
	v_pk_mul_f32 v[220:221], v[172:173], v[72:73]
	v_pk_mul_f32 v[222:223], v[174:175], v[74:75]
	v_add_f32_e32 v144, v144, v145
	v_add_f32_e32 v146, v146, v147
	v_cvt_pk_bf16_f32 v218, v220, v221
	v_cvt_pk_bf16_f32 v219, v222, v223
	v_add_f32_e32 v144, v144, v146
	v_add_f32_e32 v187, v187, v144
	s_add_u32 s22, s56, 0x40000
	s_addc_u32 s23, s57, 0
	global_store_dwordx4 v183, v[216:219], s[22:23]
	s_waitcnt lgkmcnt(0)
; __device__ __forceinline__ unsigned cvt_pk_bf16(float lo, float hi) { unsigned r; asm volatile("v_cvt_pk_bf16_f32 %0, %1, %2" : "=v"(r) : "v"(lo), "v"(hi)); return r; }
;     __device__ __forceinline__ void operator()(const f32x4 (&acc)[2][2][4][2], const Unit& u, int wr_, int wc_, int fr_, int fq_) const {
;     ...
;             for (int m = 0; m < 4; ++m) { int row = u.pm * BM + ai * HALF + wr * 64 + m * 16 + fr; asm volatile("" : "+v"(row));
;                 const size_t off = (size_t)row * 1024 + col0; float ss = 0.f;
; #pragma unroll
;                 for (int bj = 0; bj < 2; ++bj) { u32x4 w;
; #pragma unroll
;                     for (int n = 0; n < 2; ++n) { const f32x4 xi = *(const f32x4*)(xin + off + bj * HALF + n * 4);
;                         const f32x4 xn = xi + gv[bj][n] * acc[ai][bj][m][n];
;                         *(f32x4*)(xout + off + bj * HALF + n * 4) = xn;
;                         if (anext) { ss += (xn[0] * xn[0] + xn[1] * xn[1]) + (xn[2] * xn[2] + xn[3] * xn[3]);
;                             const f32x4 an = xn * sv[bj][n]; w[2 * n] = cvt_pk_bf16(an[0], an[1]); w[2 * n + 1] = cvt_pk_bf16(an[2], an[3]); } }
;                     if (anext) *(u32x4*)(anext + off + bj * HALF) = w; }
;                 if (anext) { ss += __shfl_xor(ss, 16); ss += __shfl_xor(ss, 32); if (fq == 0) atomicAdd(rss_next + row, ss); }
;                 asm volatile("" ::: "memory"); }
	v_add_f32_e32 v224, v224, v225
	ds_bpermute_b32 v225, v186, v224
	s_waitcnt vmcnt(20)
	v_pk_fma_f32 v[68:69], v[68:69], v[40:41], v[236:237]
	v_pk_fma_f32 v[70:71], v[70:71], v[42:43], v[238:239]
	s_add_u32 s22, s88, 0x80000
	s_addc_u32 s23, s89, 0
	global_store_dwordx4 v182, v[68:71], s[22:23] offset:512
	s_add_u32 s4, s10, 0xa0000
	s_addc_u32 s5, s11, 0
	global_load_dwordx4 v[236:239], v182, s[4:5] offset:512
	v_pk_mul_f32 v[144:145], v[68:69], v[68:69]
	v_pk_mul_f32 v[146:147], v[70:71], v[70:71]
	v_pk_mul_f32 v[220:221], v[168:169], v[68:69]
	v_pk_mul_f32 v[222:223], v[170:171], v[70:71]
	v_add_f32_e32 v144, v144, v145
	v_add_f32_e32 v146, v146, v147
	v_cvt_pk_bf16_f32 v194, v220, v221
	v_cvt_pk_bf16_f32 v195, v222, v223
	v_add_f32_e32 v144, v144, v146
	v_add_f32_e32 v187, v187, v144
	s_waitcnt lgkmcnt(0)
	v_add_f32_e32 v225, v224, v225
	s_and_saveexec_b64 vcc, s[6:7]
	global_atomic_add_f32 v184, v225, s[8:9] offset:192
	s_mov_b64 exec, vcc
	s_waitcnt vmcnt(20)
	v_pk_fma_f32 v[64:65], v[64:65], v[44:45], v[240:241]
	v_pk_fma_f32 v[66:67], v[66:67], v[46:47], v[242:243]
	s_add_u32 s22, s88, 0x80000
	s_addc_u32 s23, s89, 0
	global_store_dwordx4 v182, v[64:67], s[22:23] offset:528
	s_add_u32 s4, s10, 0xa0000
	s_addc_u32 s5, s11, 0
	global_load_dwordx4 v[240:243], v182, s[4:5] offset:528
	v_pk_mul_f32 v[144:145], v[64:65], v[64:65]
	v_pk_mul_f32 v[146:147], v[66:67], v[66:67]
	v_pk_mul_f32 v[220:221], v[164:165], v[64:65]
	v_pk_mul_f32 v[222:223], v[166:167], v[66:67]
	v_add_f32_e32 v144, v144, v145
	v_add_f32_e32 v146, v146, v147
	v_cvt_pk_bf16_f32 v196, v220, v221
	v_cvt_pk_bf16_f32 v197, v222, v223
	v_add_f32_e32 v144, v144, v146
	v_add_f32_e32 v187, v187, v144
	s_add_u32 s22, s56, 0x40000
	s_addc_u32 s23, s57, 0
	global_store_dwordx4 v183, v[194:197], s[22:23] offset:256
	ds_bpermute_b32 v225, v185, v187
	s_waitcnt vmcnt(20)
	v_pk_fma_f32 v[60:61], v[60:61], v[56:57], v[244:245]
	v_pk_fma_f32 v[62:63], v[62:63], v[58:59], v[246:247]
	s_add_u32 s22, s88, 0x90000
	s_addc_u32 s23, s89, 0
	global_store_dwordx4 v182, v[60:63], s[22:23]
	s_add_u32 s4, s10, 0xb0000
	s_addc_u32 s5, s11, 0
	global_load_dwordx4 v[244:247], v182, s[4:5]
	v_pk_mul_f32 v[144:145], v[60:61], v[60:61]
	v_pk_mul_f32 v[146:147], v[62:63], v[62:63]
	v_pk_mul_f32 v[220:221], v[176:177], v[60:61]
	v_pk_mul_f32 v[222:223], v[178:179], v[62:63]
	v_add_f32_e32 v144, v144, v145
	v_add_f32_e32 v146, v146, v147
	v_cvt_pk_bf16_f32 v216, v220, v221
	v_cvt_pk_bf16_f32 v217, v222, v223
	v_add_f32_e32 v224, v144, v146
	s_waitcnt vmcnt(20)
	v_pk_fma_f32 v[48:49], v[48:49], v[52:53], v[248:249]
	v_pk_fma_f32 v[50:51], v[50:51], v[54:55], v[250:251]
	s_add_u32 s22, s88, 0x90000
	s_addc_u32 s23, s89, 0
	global_store_dwordx4 v182, v[48:51], s[22:23] offset:16
	s_add_u32 s4, s10, 0xb0000
	s_addc_u32 s5, s11, 0
	global_load_dwordx4 v[248:251], v182, s[4:5] offset:16
	v_pk_mul_f32 v[144:145], v[48:49], v[48:49]
	v_pk_mul_f32 v[146:147], v[50:51], v[50:51]
	v_pk_mul_f32 v[220:221], v[172:173], v[48:49]
	v_pk_mul_f32 v[222:223], v[174:175], v[50:51]
	v_add_f32_e32 v144, v144, v145
	v_add_f32_e32 v146, v146, v147
	v_cvt_pk_bf16_f32 v218, v220, v221
	v_cvt_pk_bf16_f32 v219, v222, v223
	v_add_f32_e32 v144, v144, v146
	v_add_f32_e32 v224, v224, v144
	s_add_u32 s22, s56, 0x48000
	s_addc_u32 s23, s57, 0
	global_store_dwordx4 v183, v[216:219], s[22:23]
	s_waitcnt lgkmcnt(0)
	v_add_f32_e32 v187, v187, v225
	ds_bpermute_b32 v225, v186, v187
	s_waitcnt vmcnt(20)
	v_pk_fma_f32 v[36:37], v[36:37], v[40:41], v[208:209]
	v_pk_fma_f32 v[38:39], v[38:39], v[42:43], v[210:211]
	s_add_u32 s22, s88, 0x90000
	s_addc_u32 s23, s89, 0
	global_store_dwordx4 v182, v[36:39], s[22:23] offset:512
	s_add_u32 s4, s10, 0xb0000
	s_addc_u32 s5, s11, 0
	global_load_dwordx4 v[208:211], v182, s[4:5] offset:512
	v_pk_mul_f32 v[144:145], v[36:37], v[36:37]
	v_pk_mul_f32 v[146:147], v[38:39], v[38:39]
	v_pk_mul_f32 v[220:221], v[168:169], v[36:37]
	v_pk_mul_f32 v[222:223], v[170:171], v[38:39]
	v_add_f32_e32 v144, v144, v145
	v_add_f32_e32 v146, v146, v147
	v_cvt_pk_bf16_f32 v194, v220, v221
	v_cvt_pk_bf16_f32 v195, v222, v223
	v_add_f32_e32 v144, v144, v146
	v_add_f32_e32 v224, v224, v144
	s_waitcnt lgkmcnt(0)
	v_add_f32_e32 v225, v187, v225
	s_and_saveexec_b64 vcc, s[6:7]
	global_atomic_add_f32 v184, v225, s[8:9] offset:512
	s_mov_b64 exec, vcc
	s_waitcnt vmcnt(20)
	v_pk_fma_f32 v[32:33], v[32:33], v[44:45], v[212:213]
	v_pk_fma_f32 v[34:35], v[34:35], v[46:47], v[214:215]
	s_add_u32 s22, s88, 0x90000
	s_addc_u32 s23, s89, 0
	global_store_dwordx4 v182, v[32:35], s[22:23] offset:528
	s_add_u32 s4, s10, 0xb0000
	s_addc_u32 s5, s11, 0
	global_load_dwordx4 v[212:215], v182, s[4:5] offset:528
	v_pk_mul_f32 v[144:145], v[32:33], v[32:33]
	v_pk_mul_f32 v[146:147], v[34:35], v[34:35]
	v_pk_mul_f32 v[220:221], v[164:165], v[32:33]
	v_pk_mul_f32 v[222:223], v[166:167], v[34:35]
	v_add_f32_e32 v144, v144, v145
	v_add_f32_e32 v146, v146, v147
	v_cvt_pk_bf16_f32 v196, v220, v221
	v_cvt_pk_bf16_f32 v197, v222, v223
	v_add_f32_e32 v144, v144, v146
	v_add_f32_e32 v224, v224, v144
	s_add_u32 s22, s56, 0x48000
	s_addc_u32 s23, s57, 0
	global_store_dwordx4 v183, v[194:197], s[22:23] offset:256
	ds_bpermute_b32 v225, v185, v224
	s_waitcnt vmcnt(20)
	v_pk_fma_f32 v[28:29], v[28:29], v[56:57], v[228:229]
	v_pk_fma_f32 v[30:31], v[30:31], v[58:59], v[230:231]
	s_add_u32 s22, s88, 0xa0000
	s_addc_u32 s23, s89, 0
	global_store_dwordx4 v182, v[28:31], s[22:23]
	v_pk_mul_f32 v[144:145], v[28:29], v[28:29]
	v_pk_mul_f32 v[146:147], v[30:31], v[30:31]
	v_pk_mul_f32 v[220:221], v[176:177], v[28:29]
	v_pk_mul_f32 v[222:223], v[178:179], v[30:31]
	v_add_f32_e32 v144, v144, v145
	v_add_f32_e32 v146, v146, v147
	v_cvt_pk_bf16_f32 v216, v220, v221
	v_cvt_pk_bf16_f32 v217, v222, v223
	v_add_f32_e32 v187, v144, v146
	s_waitcnt vmcnt(19)
; __device__ __forceinline__ unsigned cvt_pk_bf16(float lo, float hi) { unsigned r; asm volatile("v_cvt_pk_bf16_f32 %0, %1, %2" : "=v"(r) : "v"(lo), "v"(hi)); return r; }
;     __device__ __forceinline__ void operator()(const f32x4 (&acc)[2][2][4][2], const Unit& u, int wr_, int wc_, int fr_, int fq_) const {
;     ...
;             for (int m = 0; m < 4; ++m) { int row = u.pm * BM + ai * HALF + wr * 64 + m * 16 + fr; asm volatile("" : "+v"(row));
;                 const size_t off = (size_t)row * 1024 + col0; float ss = 0.f;
; #pragma unroll
;                 for (int bj = 0; bj < 2; ++bj) { u32x4 w;
; #pragma unroll
;                     for (int n = 0; n < 2; ++n) { const f32x4 xi = *(const f32x4*)(xin + off + bj * HALF + n * 4);
;                         const f32x4 xn = xi + gv[bj][n] * acc[ai][bj][m][n];
;                         *(f32x4*)(xout + off + bj * HALF + n * 4) = xn;
;                         if (anext) { ss += (xn[0] * xn[0] + xn[1] * xn[1]) + (xn[2] * xn[2] + xn[3] * xn[3]);
;                             const f32x4 an = xn * sv[bj][n]; w[2 * n] = cvt_pk_bf16(an[0], an[1]); w[2 * n + 1] = cvt_pk_bf16(an[2], an[3]); } }
;                     if (anext) *(u32x4*)(anext + off + bj * HALF) = w; }
;                 if (anext) { ss += __shfl_xor(ss, 16); ss += __shfl_xor(ss, 32); if (fq == 0) atomicAdd(rss_next + row, ss); }
;                 asm volatile("" ::: "memory"); }
	v_pk_fma_f32 v[24:25], v[24:25], v[52:53], v[232:233]
	v_pk_fma_f32 v[26:27], v[26:27], v[54:55], v[234:235]
	s_add_u32 s22, s88, 0xa0000
	s_addc_u32 s23, s89, 0
	global_store_dwordx4 v182, v[24:27], s[22:23] offset:16
	v_pk_mul_f32 v[144:145], v[24:25], v[24:25]
	v_pk_mul_f32 v[146:147], v[26:27], v[26:27]
	v_pk_mul_f32 v[220:221], v[172:173], v[24:25]
	v_pk_mul_f32 v[222:223], v[174:175], v[26:27]
	v_add_f32_e32 v144, v144, v145
	v_add_f32_e32 v146, v146, v147
	v_cvt_pk_bf16_f32 v218, v220, v221
	v_cvt_pk_bf16_f32 v219, v222, v223
	v_add_f32_e32 v144, v144, v146
	v_add_f32_e32 v187, v187, v144
	s_add_u32 s22, s56, 0x50000
	s_addc_u32 s23, s57, 0
	global_store_dwordx4 v183, v[216:219], s[22:23]
	s_waitcnt lgkmcnt(0)
	v_add_f32_e32 v224, v224, v225
	ds_bpermute_b32 v225, v186, v224
	s_waitcnt vmcnt(18)
	v_pk_fma_f32 v[20:21], v[20:21], v[40:41], v[236:237]
	v_pk_fma_f32 v[22:23], v[22:23], v[42:43], v[238:239]
	s_add_u32 s22, s88, 0xa0000
	s_addc_u32 s23, s89, 0
	global_store_dwordx4 v182, v[20:23], s[22:23] offset:512
	v_pk_mul_f32 v[144:145], v[20:21], v[20:21]
	v_pk_mul_f32 v[146:147], v[22:23], v[22:23]
	v_pk_mul_f32 v[220:221], v[168:169], v[20:21]
	v_pk_mul_f32 v[222:223], v[170:171], v[22:23]
	v_add_f32_e32 v144, v144, v145
	v_add_f32_e32 v146, v146, v147
	v_cvt_pk_bf16_f32 v194, v220, v221
	v_cvt_pk_bf16_f32 v195, v222, v223
	v_add_f32_e32 v144, v144, v146
	v_add_f32_e32 v187, v187, v144
	s_waitcnt lgkmcnt(0)
	v_add_f32_e32 v225, v224, v225
	s_and_saveexec_b64 vcc, s[6:7]
	global_atomic_add_f32 v184, v225, s[8:9] offset:576
	s_mov_b64 exec, vcc
	s_waitcnt vmcnt(17)
	v_pk_fma_f32 v[16:17], v[16:17], v[44:45], v[240:241]
	v_pk_fma_f32 v[18:19], v[18:19], v[46:47], v[242:243]
	s_add_u32 s22, s88, 0xa0000
	s_addc_u32 s23, s89, 0
	global_store_dwordx4 v182, v[16:19], s[22:23] offset:528
	v_pk_mul_f32 v[144:145], v[16:17], v[16:17]
	v_pk_mul_f32 v[146:147], v[18:19], v[18:19]
	v_pk_mul_f32 v[220:221], v[164:165], v[16:17]
	v_pk_mul_f32 v[222:223], v[166:167], v[18:19]
	v_add_f32_e32 v144, v144, v145
	v_add_f32_e32 v146, v146, v147
	v_cvt_pk_bf16_f32 v196, v220, v221
	v_cvt_pk_bf16_f32 v197, v222, v223
	v_add_f32_e32 v144, v144, v146
	v_add_f32_e32 v187, v187, v144
	s_add_u32 s22, s56, 0x50000
	s_addc_u32 s23, s57, 0
	global_store_dwordx4 v183, v[194:197], s[22:23] offset:256
	ds_bpermute_b32 v225, v185, v187
	s_waitcnt vmcnt(16)
	v_pk_fma_f32 v[12:13], v[12:13], v[56:57], v[244:245]
	v_pk_fma_f32 v[14:15], v[14:15], v[58:59], v[246:247]
	s_add_u32 s22, s88, 0xb0000
	s_addc_u32 s23, s89, 0
	global_store_dwordx4 v182, v[12:15], s[22:23]
	v_pk_mul_f32 v[144:145], v[12:13], v[12:13]
	v_pk_mul_f32 v[146:147], v[14:15], v[14:15]
	v_pk_mul_f32 v[220:221], v[176:177], v[12:13]
	v_pk_mul_f32 v[222:223], v[178:179], v[14:15]
	v_add_f32_e32 v144, v144, v145
	v_add_f32_e32 v146, v146, v147
	v_cvt_pk_bf16_f32 v216, v220, v221
	v_cvt_pk_bf16_f32 v217, v222, v223
	v_add_f32_e32 v224, v144, v146
	s_waitcnt vmcnt(15)
	v_pk_fma_f32 v[8:9], v[8:9], v[52:53], v[248:249]
	v_pk_fma_f32 v[10:11], v[10:11], v[54:55], v[250:251]
	s_add_u32 s22, s88, 0xb0000
	s_addc_u32 s23, s89, 0
	global_store_dwordx4 v182, v[8:11], s[22:23] offset:16
	v_pk_mul_f32 v[144:145], v[8:9], v[8:9]
	v_pk_mul_f32 v[146:147], v[10:11], v[10:11]
	v_pk_mul_f32 v[220:221], v[172:173], v[8:9]
	v_pk_mul_f32 v[222:223], v[174:175], v[10:11]
	v_add_f32_e32 v144, v144, v145
	v_add_f32_e32 v146, v146, v147
	v_cvt_pk_bf16_f32 v218, v220, v221
	v_cvt_pk_bf16_f32 v219, v222, v223
	v_add_f32_e32 v144, v144, v146
	v_add_f32_e32 v224, v224, v144
	s_add_u32 s22, s56, 0x58000
	s_addc_u32 s23, s57, 0
	global_store_dwordx4 v183, v[216:219], s[22:23]
	s_waitcnt lgkmcnt(0)
	v_add_f32_e32 v187, v187, v225
	ds_bpermute_b32 v225, v186, v187
	s_waitcnt vmcnt(14)
	v_pk_fma_f32 v[4:5], v[4:5], v[40:41], v[208:209]
	v_pk_fma_f32 v[6:7], v[6:7], v[42:43], v[210:211]
	s_add_u32 s22, s88, 0xb0000
	s_addc_u32 s23, s89, 0
	global_store_dwordx4 v182, v[4:7], s[22:23] offset:512
	v_pk_mul_f32 v[144:145], v[4:5], v[4:5]
	v_pk_mul_f32 v[146:147], v[6:7], v[6:7]
	v_pk_mul_f32 v[220:221], v[168:169], v[4:5]
	v_pk_mul_f32 v[222:223], v[170:171], v[6:7]
	v_add_f32_e32 v144, v144, v145
	v_add_f32_e32 v146, v146, v147
	v_cvt_pk_bf16_f32 v194, v220, v221
	v_cvt_pk_bf16_f32 v195, v222, v223
	v_add_f32_e32 v144, v144, v146
	v_add_f32_e32 v224, v224, v144
	s_waitcnt lgkmcnt(0)
	v_add_f32_e32 v225, v187, v225
	s_and_saveexec_b64 vcc, s[6:7]
	global_atomic_add_f32 v184, v225, s[8:9] offset:640
	s_mov_b64 exec, vcc
	s_waitcnt vmcnt(13)
	v_pk_fma_f32 v[0:1], v[0:1], v[44:45], v[212:213]
	v_pk_fma_f32 v[2:3], v[2:3], v[46:47], v[214:215]
	s_add_u32 s22, s88, 0xb0000
	s_addc_u32 s23, s89, 0
	global_store_dwordx4 v182, v[0:3], s[22:23] offset:528
	v_pk_mul_f32 v[144:145], v[0:1], v[0:1]
	v_pk_mul_f32 v[146:147], v[2:3], v[2:3]
	v_pk_mul_f32 v[220:221], v[164:165], v[0:1]
	v_pk_mul_f32 v[222:223], v[166:167], v[2:3]
	v_add_f32_e32 v144, v144, v145
	v_add_f32_e32 v146, v146, v147
	v_cvt_pk_bf16_f32 v196, v220, v221
	v_cvt_pk_bf16_f32 v197, v222, v223
	v_add_f32_e32 v144, v144, v146
	v_add_f32_e32 v224, v224, v144
	s_add_u32 s22, s56, 0x58000
	s_addc_u32 s23, s57, 0
	global_store_dwordx4 v183, v[194:197], s[22:23] offset:256
	ds_bpermute_b32 v225, v185, v224
	s_waitcnt lgkmcnt(0)
	v_add_f32_e32 v224, v224, v225
	ds_bpermute_b32 v225, v186, v224
	s_waitcnt lgkmcnt(0)
	v_add_f32_e32 v225, v224, v225
	s_and_saveexec_b64 vcc, s[6:7]
	global_atomic_add_f32 v184, v225, s[8:9] offset:704
	s_mov_b64 exec, vcc
	s_branch .LBB0_1066
;     __device__ __forceinline__ void operator()(const f32x4 (&acc)[2][2][4][2], const Unit& u, int wr_, int wc_, int fr_, int fq_) const {
;     ...
;         const int b = u.pm >> 5;
;         const int col0 = u.pn * BM + wc * 32 + 8 * fq;
;         const float* gp = gate + (size_t)b * 6144 + col0;
;         f32x4 gv[2][2], sv[2][2];
; #pragma unroll
;         for (int bj = 0; bj < 2; ++bj)
; #pragma unroll
;             for (int n = 0; n < 2; ++n) { gv[bj][n] = *(const f32x4*)(gp + bj * HALF + n * 4);
;                 sv[bj][n] = anext ? *(const f32x4*)(scale_next + (size_t)b * 6144 + col0 + bj * HALF + n * 4) + 1.0f : (f32x4){0.f, 0.f, 0.f, 0.f}; }
; #pragma unroll
;         for (int ai = 0; ai < 2; ++ai)
; #pragma unroll
;             for (int m = 0; m < 4; ++m) { int row = u.pm * BM + ai * HALF + wr * 64 + m * 16 + fr; asm volatile("" : "+v"(row));
;                 const size_t off = (size_t)row * 1024 + col0; float ss = 0.f;
; #pragma unroll
;                 for (int bj = 0; bj < 2; ++bj) { u32x4 w;
; #pragma unroll
;                     for (int n = 0; n < 2; ++n) { const f32x4 xi = *(const f32x4*)(xin + off + bj * HALF + n * 4);
;                         const f32x4 xn = xi + gv[bj][n] * acc[ai][bj][m][n];
;                         *(f32x4*)(xout + off + bj * HALF + n * 4) = xn;
.Lrg4_fastn:
	s_movk_i32 s49, 0x4000
	s_mov_b32 s51, 0x10000
	s_mov_b32 s52, 0x14000
	v_bfe_u32 v227, v190, 4, 2
	v_lshrrev_b32_e32 v144, 1, v190
	v_and_b32_e32 v144, 0x60, v144
	s_lshl_b32 s6, s43, 8
	v_lshlrev_b32_e32 v145, 3, v227
	v_or3_b32 v180, v144, s6, v145
	v_lshlrev_b32_e32 v181, 2, v180
	s_ashr_i32 s6, s33, 5
	s_mul_i32 s6, s6, 0x6000
	s_add_u32 s4, s35, s6
	s_addc_u32 s5, s36, 0
	global_load_dwordx4 v[56:59], v181, s[4:5]
	global_load_dwordx4 v[52:55], v181, s[4:5] offset:16
	global_load_dwordx4 v[40:43], v181, s[4:5] offset:512
	global_load_dwordx4 v[44:47], v181, s[4:5] offset:528
	s_lshl_b32 s6, s33, 8
	v_ashrrev_i32_e32 v144, 2, v190
	v_and_b32_e32 v144, 0xffffffc0, v144
	v_and_or_b32 v145, v190, 15, s6
	v_add_u32_e32 v184, v145, v144
	v_lshl_add_u32 v182, v184, 10, v180
	v_lshlrev_b32_e32 v182, 2, v182
	global_load_dwordx4 v[228:231], v182, s[10:11]
	global_load_dwordx4 v[232:235], v182, s[10:11] offset:16
	global_load_dwordx4 v[236:239], v182, s[10:11] offset:512
	global_load_dwordx4 v[240:243], v182, s[10:11] offset:528
	s_add_u32 s4, s10, 0x10000
	s_addc_u32 s5, s11, 0
	global_load_dwordx4 v[244:247], v182, s[4:5]
	s_add_u32 s4, s10, 0x10000
	s_addc_u32 s5, s11, 0
	global_load_dwordx4 v[248:251], v182, s[4:5] offset:16
	s_add_u32 s4, s10, 0x10000
	s_addc_u32 s5, s11, 0
	global_load_dwordx4 v[208:211], v182, s[4:5] offset:512
	s_add_u32 s4, s10, 0x10000
	s_addc_u32 s5, s11, 0
	global_load_dwordx4 v[212:215], v182, s[4:5] offset:528
	s_waitcnt vmcnt(8)
	s_waitcnt vmcnt(7)
	v_pk_fma_f32 v[140:141], v[140:141], v[56:57], v[228:229]
	v_pk_fma_f32 v[142:143], v[142:143], v[58:59], v[230:231]
	global_store_dwordx4 v182, v[140:143], s[88:89]
	s_add_u32 s4, s10, 0x20000
	s_addc_u32 s5, s11, 0
	global_load_dwordx4 v[228:231], v182, s[4:5]
	s_waitcnt vmcnt(8)
	v_pk_fma_f32 v[136:137], v[136:137], v[52:53], v[232:233]
	v_pk_fma_f32 v[138:139], v[138:139], v[54:55], v[234:235]
	global_store_dwordx4 v182, v[136:139], s[88:89] offset:16
	s_add_u32 s4, s10, 0x20000
	s_addc_u32 s5, s11, 0
	global_load_dwordx4 v[232:235], v182, s[4:5] offset:16
	s_waitcnt vmcnt(9)
	v_pk_fma_f32 v[132:133], v[132:133], v[40:41], v[236:237]
	v_pk_fma_f32 v[134:135], v[134:135], v[42:43], v[238:239]
	global_store_dwordx4 v182, v[132:135], s[88:89] offset:512
	s_add_u32 s4, s10, 0x20000
	s_addc_u32 s5, s11, 0
	global_load_dwordx4 v[236:239], v182, s[4:5] offset:512
	s_waitcnt vmcnt(10)
	v_pk_fma_f32 v[128:129], v[128:129], v[44:45], v[240:241]
	v_pk_fma_f32 v[130:131], v[130:131], v[46:47], v[242:243]
	global_store_dwordx4 v182, v[128:131], s[88:89] offset:528
	s_add_u32 s4, s10, 0x20000
	s_addc_u32 s5, s11, 0
	global_load_dwordx4 v[240:243], v182, s[4:5] offset:528
	s_waitcnt vmcnt(11)
	v_pk_fma_f32 v[124:125], v[124:125], v[56:57], v[244:245]
	v_pk_fma_f32 v[126:127], v[126:127], v[58:59], v[246:247]
	s_add_u32 s22, s88, 0x10000
	s_addc_u32 s23, s89, 0
	global_store_dwordx4 v182, v[124:127], s[22:23]
	s_add_u32 s4, s10, 0x30000
	s_addc_u32 s5, s11, 0
	global_load_dwordx4 v[244:247], v182, s[4:5]
	s_waitcnt vmcnt(12)
	v_pk_fma_f32 v[120:121], v[120:121], v[52:53], v[248:249]
	v_pk_fma_f32 v[122:123], v[122:123], v[54:55], v[250:251]
	s_add_u32 s22, s88, 0x10000
	s_addc_u32 s23, s89, 0
	global_store_dwordx4 v182, v[120:123], s[22:23] offset:16
	s_add_u32 s4, s10, 0x30000
	s_addc_u32 s5, s11, 0
	global_load_dwordx4 v[248:251], v182, s[4:5] offset:16
	s_waitcnt vmcnt(13)
	v_pk_fma_f32 v[116:117], v[116:117], v[40:41], v[208:209]
	v_pk_fma_f32 v[118:119], v[118:119], v[42:43], v[210:211]
	s_add_u32 s22, s88, 0x10000
	s_addc_u32 s23, s89, 0
	global_store_dwordx4 v182, v[116:119], s[22:23] offset:512
	s_add_u32 s4, s10, 0x30000
	s_addc_u32 s5, s11, 0
	global_load_dwordx4 v[208:211], v182, s[4:5] offset:512
	s_waitcnt vmcnt(14)
	v_pk_fma_f32 v[112:113], v[112:113], v[44:45], v[212:213]
	v_pk_fma_f32 v[114:115], v[114:115], v[46:47], v[214:215]
	s_add_u32 s22, s88, 0x10000
	s_addc_u32 s23, s89, 0
	global_store_dwordx4 v182, v[112:115], s[22:23] offset:528
	s_add_u32 s4, s10, 0x30000
	s_addc_u32 s5, s11, 0
	global_load_dwordx4 v[212:215], v182, s[4:5] offset:528
	s_waitcnt vmcnt(14)
	v_pk_fma_f32 v[108:109], v[108:109], v[56:57], v[228:229]
	v_pk_fma_f32 v[110:111], v[110:111], v[58:59], v[230:231]
	s_add_u32 s22, s88, 0x20000
	s_addc_u32 s23, s89, 0
	global_store_dwordx4 v182, v[108:111], s[22:23]
	s_add_u32 s4, s10, 0x80000
	s_addc_u32 s5, s11, 0
	global_load_dwordx4 v[228:231], v182, s[4:5]
	s_waitcnt vmcnt(14)
	v_pk_fma_f32 v[104:105], v[104:105], v[52:53], v[232:233]
	v_pk_fma_f32 v[106:107], v[106:107], v[54:55], v[234:235]
	s_add_u32 s22, s88, 0x20000
	s_addc_u32 s23, s89, 0
	global_store_dwordx4 v182, v[104:107], s[22:23] offset:16
	s_add_u32 s4, s10, 0x80000
	s_addc_u32 s5, s11, 0
	global_load_dwordx4 v[232:235], v182, s[4:5] offset:16
	s_waitcnt vmcnt(14)
	v_pk_fma_f32 v[100:101], v[100:101], v[40:41], v[236:237]
	v_pk_fma_f32 v[102:103], v[102:103], v[42:43], v[238:239]
	s_add_u32 s22, s88, 0x20000
	s_addc_u32 s23, s89, 0
	global_store_dwordx4 v182, v[100:103], s[22:23] offset:512
	s_add_u32 s4, s10, 0x80000
	s_addc_u32 s5, s11, 0
	global_load_dwordx4 v[236:239], v182, s[4:5] offset:512
	s_waitcnt vmcnt(14)
	v_pk_fma_f32 v[96:97], v[96:97], v[44:45], v[240:241]
	v_pk_fma_f32 v[98:99], v[98:99], v[46:47], v[242:243]
	s_add_u32 s22, s88, 0x20000
	s_addc_u32 s23, s89, 0
	global_store_dwordx4 v182, v[96:99], s[22:23] offset:528
	s_add_u32 s4, s10, 0x80000
	s_addc_u32 s5, s11, 0
	global_load_dwordx4 v[240:243], v182, s[4:5] offset:528
	s_waitcnt vmcnt(14)
;     __device__ __forceinline__ void operator()(const f32x4 (&acc)[2][2][4][2], const Unit& u, int wr_, int wc_, int fr_, int fq_) const {
;     ...
;         const int b = u.pm >> 5;
;         const int col0 = u.pn * BM + wc * 32 + 8 * fq;
;         const float* gp = gate + (size_t)b * 6144 + col0;
;         f32x4 gv[2][2], sv[2][2];
; #pragma unroll
;         for (int bj = 0; bj < 2; ++bj)
; #pragma unroll
;             for (int n = 0; n < 2; ++n) { gv[bj][n] = *(const f32x4*)(gp + bj * HALF + n * 4);
;                 sv[bj][n] = anext ? *(const f32x4*)(scale_next + (size_t)b * 6144 + col0 + bj * HALF + n * 4) + 1.0f : (f32x4){0.f, 0.f, 0.f, 0.f}; }
; #pragma unroll
;         for (int ai = 0; ai < 2; ++ai)
; #pragma unroll
;             for (int m = 0; m < 4; ++m) { int row = u.pm * BM + ai * HALF + wr * 64 + m * 16 + fr; asm volatile("" : "+v"(row));
;                 const size_t off = (size_t)row * 1024 + col0; float ss = 0.f;
; #pragma unroll
;                 for (int bj = 0; bj < 2; ++bj) { u32x4 w;
; #pragma unroll
;                     for (int n = 0; n < 2; ++n) { const f32x4 xi = *(const f32x4*)(xin + off + bj * HALF + n * 4);
;                         const f32x4 xn = xi + gv[bj][n] * acc[ai][bj][m][n];
;                         *(f32x4*)(xout + off + bj * HALF + n * 4) = xn;
	v_pk_fma_f32 v[92:93], v[92:93], v[56:57], v[244:245]
	v_pk_fma_f32 v[94:95], v[94:95], v[58:59], v[246:247]
	s_add_u32 s22, s88, 0x30000
	s_addc_u32 s23, s89, 0
	global_store_dwordx4 v182, v[92:95], s[22:23]
	s_add_u32 s4, s10, 0x90000
	s_addc_u32 s5, s11, 0
	global_load_dwordx4 v[244:247], v182, s[4:5]
	s_waitcnt vmcnt(14)
	v_pk_fma_f32 v[88:89], v[88:89], v[52:53], v[248:249]
	v_pk_fma_f32 v[90:91], v[90:91], v[54:55], v[250:251]
	s_add_u32 s22, s88, 0x30000
	s_addc_u32 s23, s89, 0
	global_store_dwordx4 v182, v[88:91], s[22:23] offset:16
	s_add_u32 s4, s10, 0x90000
	s_addc_u32 s5, s11, 0
	global_load_dwordx4 v[248:251], v182, s[4:5] offset:16
	s_waitcnt vmcnt(14)
	v_pk_fma_f32 v[84:85], v[84:85], v[40:41], v[208:209]
	v_pk_fma_f32 v[86:87], v[86:87], v[42:43], v[210:211]
	s_add_u32 s22, s88, 0x30000
	s_addc_u32 s23, s89, 0
	global_store_dwordx4 v182, v[84:87], s[22:23] offset:512
	s_add_u32 s4, s10, 0x90000
	s_addc_u32 s5, s11, 0
	global_load_dwordx4 v[208:211], v182, s[4:5] offset:512
	s_waitcnt vmcnt(14)
	v_pk_fma_f32 v[80:81], v[80:81], v[44:45], v[212:213]
	v_pk_fma_f32 v[82:83], v[82:83], v[46:47], v[214:215]
	s_add_u32 s22, s88, 0x30000
	s_addc_u32 s23, s89, 0
	global_store_dwordx4 v182, v[80:83], s[22:23] offset:528
	s_add_u32 s4, s10, 0x90000
	s_addc_u32 s5, s11, 0
	global_load_dwordx4 v[212:215], v182, s[4:5] offset:528
	s_waitcnt vmcnt(14)
	v_pk_fma_f32 v[76:77], v[76:77], v[56:57], v[228:229]
	v_pk_fma_f32 v[78:79], v[78:79], v[58:59], v[230:231]
	s_add_u32 s22, s88, 0x80000
	s_addc_u32 s23, s89, 0
	global_store_dwordx4 v182, v[76:79], s[22:23]
	s_add_u32 s4, s10, 0xa0000
	s_addc_u32 s5, s11, 0
	global_load_dwordx4 v[228:231], v182, s[4:5]
	s_waitcnt vmcnt(14)
	v_pk_fma_f32 v[72:73], v[72:73], v[52:53], v[232:233]
	v_pk_fma_f32 v[74:75], v[74:75], v[54:55], v[234:235]
	s_add_u32 s22, s88, 0x80000
	s_addc_u32 s23, s89, 0
	global_store_dwordx4 v182, v[72:75], s[22:23] offset:16
	s_add_u32 s4, s10, 0xa0000
	s_addc_u32 s5, s11, 0
	global_load_dwordx4 v[232:235], v182, s[4:5] offset:16
	s_waitcnt vmcnt(14)
	v_pk_fma_f32 v[68:69], v[68:69], v[40:41], v[236:237]
	v_pk_fma_f32 v[70:71], v[70:71], v[42:43], v[238:239]
	s_add_u32 s22, s88, 0x80000
	s_addc_u32 s23, s89, 0
	global_store_dwordx4 v182, v[68:71], s[22:23] offset:512
	s_add_u32 s4, s10, 0xa0000
	s_addc_u32 s5, s11, 0
	global_load_dwordx4 v[236:239], v182, s[4:5] offset:512
	s_waitcnt vmcnt(14)
	v_pk_fma_f32 v[64:65], v[64:65], v[44:45], v[240:241]
	v_pk_fma_f32 v[66:67], v[66:67], v[46:47], v[242:243]
	s_add_u32 s22, s88, 0x80000
	s_addc_u32 s23, s89, 0
	global_store_dwordx4 v182, v[64:67], s[22:23] offset:528
	s_add_u32 s4, s10, 0xa0000
	s_addc_u32 s5, s11, 0
	global_load_dwordx4 v[240:243], v182, s[4:5] offset:528
	s_waitcnt vmcnt(14)
	v_pk_fma_f32 v[60:61], v[60:61], v[56:57], v[244:245]
	v_pk_fma_f32 v[62:63], v[62:63], v[58:59], v[246:247]
	s_add_u32 s22, s88, 0x90000
	s_addc_u32 s23, s89, 0
	global_store_dwordx4 v182, v[60:63], s[22:23]
	s_add_u32 s4, s10, 0xb0000
	s_addc_u32 s5, s11, 0
	global_load_dwordx4 v[244:247], v182, s[4:5]
	s_waitcnt vmcnt(14)
	v_pk_fma_f32 v[48:49], v[48:49], v[52:53], v[248:249]
	v_pk_fma_f32 v[50:51], v[50:51], v[54:55], v[250:251]
	s_add_u32 s22, s88, 0x90000
	s_addc_u32 s23, s89, 0
	global_store_dwordx4 v182, v[48:51], s[22:23] offset:16
	s_add_u32 s4, s10, 0xb0000
	s_addc_u32 s5, s11, 0
	global_load_dwordx4 v[248:251], v182, s[4:5] offset:16
	s_waitcnt vmcnt(14)
	v_pk_fma_f32 v[36:37], v[36:37], v[40:41], v[208:209]
	v_pk_fma_f32 v[38:39], v[38:39], v[42:43], v[210:211]
	s_add_u32 s22, s88, 0x90000
	s_addc_u32 s23, s89, 0
	global_store_dwordx4 v182, v[36:39], s[22:23] offset:512
	s_add_u32 s4, s10, 0xb0000
	s_addc_u32 s5, s11, 0
	global_load_dwordx4 v[208:211], v182, s[4:5] offset:512
	s_waitcnt vmcnt(14)
	v_pk_fma_f32 v[32:33], v[32:33], v[44:45], v[212:213]
	v_pk_fma_f32 v[34:35], v[34:35], v[46:47], v[214:215]
	s_add_u32 s22, s88, 0x90000
	s_addc_u32 s23, s89, 0
	global_store_dwordx4 v182, v[32:35], s[22:23] offset:528
	s_add_u32 s4, s10, 0xb0000
	s_addc_u32 s5, s11, 0
	global_load_dwordx4 v[212:215], v182, s[4:5] offset:528
	s_waitcnt vmcnt(14)
	v_pk_fma_f32 v[28:29], v[28:29], v[56:57], v[228:229]
	v_pk_fma_f32 v[30:31], v[30:31], v[58:59], v[230:231]
	s_add_u32 s22, s88, 0xa0000
	s_addc_u32 s23, s89, 0
	global_store_dwordx4 v182, v[28:31], s[22:23]
	s_waitcnt vmcnt(13)
	v_pk_fma_f32 v[24:25], v[24:25], v[52:53], v[232:233]
	v_pk_fma_f32 v[26:27], v[26:27], v[54:55], v[234:235]
	s_add_u32 s22, s88, 0xa0000
	s_addc_u32 s23, s89, 0
	global_store_dwordx4 v182, v[24:27], s[22:23] offset:16
	s_waitcnt vmcnt(12)
	v_pk_fma_f32 v[20:21], v[20:21], v[40:41], v[236:237]
	v_pk_fma_f32 v[22:23], v[22:23], v[42:43], v[238:239]
	s_add_u32 s22, s88, 0xa0000
	s_addc_u32 s23, s89, 0
	global_store_dwordx4 v182, v[20:23], s[22:23] offset:512
	s_waitcnt vmcnt(11)
	v_pk_fma_f32 v[16:17], v[16:17], v[44:45], v[240:241]
	v_pk_fma_f32 v[18:19], v[18:19], v[46:47], v[242:243]
	s_add_u32 s22, s88, 0xa0000
	s_addc_u32 s23, s89, 0
	global_store_dwordx4 v182, v[16:19], s[22:23] offset:528
	s_waitcnt vmcnt(10)
	v_pk_fma_f32 v[12:13], v[12:13], v[56:57], v[244:245]
	v_pk_fma_f32 v[14:15], v[14:15], v[58:59], v[246:247]
	s_add_u32 s22, s88, 0xb0000
	s_addc_u32 s23, s89, 0
	global_store_dwordx4 v182, v[12:15], s[22:23]
	s_waitcnt vmcnt(9)
	v_pk_fma_f32 v[8:9], v[8:9], v[52:53], v[248:249]
	v_pk_fma_f32 v[10:11], v[10:11], v[54:55], v[250:251]
	s_add_u32 s22, s88, 0xb0000
	s_addc_u32 s23, s89, 0
	global_store_dwordx4 v182, v[8:11], s[22:23] offset:16
	s_waitcnt vmcnt(8)
	v_pk_fma_f32 v[4:5], v[4:5], v[40:41], v[208:209]
	v_pk_fma_f32 v[6:7], v[6:7], v[42:43], v[210:211]
	s_add_u32 s22, s88, 0xb0000
	s_addc_u32 s23, s89, 0
	global_store_dwordx4 v182, v[4:7], s[22:23] offset:512
	s_waitcnt vmcnt(7)
	v_pk_fma_f32 v[0:1], v[0:1], v[44:45], v[212:213]
	v_pk_fma_f32 v[2:3], v[2:3], v[46:47], v[214:215]
	s_add_u32 s22, s88, 0xb0000
	s_addc_u32 s23, s89, 0
	global_store_dwordx4 v182, v[0:3], s[22:23] offset:528
	s_branch .LBB0_1066

; #define PG8_STAGE(bufoff, gbase, voff) do { _Pragma("unroll") for (int _i = 0; _i < 2; ++_i) \
;         __builtin_amdgcn_global_load_lds((const unsigned*)((const char*)(gbase) + (voff)[_i]), (PG8_LAS unsigned*)(lds + (bufoff) + ldsw + _i * 8192), 16, 0, 0); } while (0)
; #define PG8_LDA(dst, b, h) do { _Pragma("unroll") for (int m = 0; m < 4; ++m) _Pragma("unroll") for (int k = 0; k < 2; ++k) dst[m][k] = *(const PG8_LAS bf16x8*)(lds + PG8_SA(b, h) + aoff + m * 2048 + k * 1024); } while (0)
; #define PG8_LDB(dst, b, h) do { _Pragma("unroll") for (int n = 0; n < 2; ++n) _Pragma("unroll") for (int k = 0; k < 2; ++k) dst[n][k] = *(const PG8_LAS bf16x8*)(lds + PG8_SB(b, h) + boff + n * 2048 + k * 1024); } while (0)
; #define PG8_MMA(ai, bj, At, Bt) do { __builtin_amdgcn_s_setprio(1); _Pragma("unroll") for (int m = 0; m < 4; ++m) _Pragma("unroll") for (int n = 0; n < 2; ++n) _Pragma("unroll") for (int k = 0; k < 2; ++k) \
;         acc[ai][bj][m][n] = __builtin_amdgcn_mfma_f32_16x16x32_bf16(Bt[n][k], At[m][k], acc[ai][bj][m][n], 0, 0, 0); __builtin_amdgcn_s_setprio(0); } while (0)
; #define PG8_WAIT_V(n) asm volatile("s_waitcnt vmcnt(" #n ")" ::: "memory")
; template <class Epi, class Sched, bool ALIGN_EPI = false, bool SP2 = false>
; __device__ __forceinline__ void gemm_phase(PG8_LAS unsigned char* lds, const Gemm g, const Sched& S, const Epi& E) {
;     ...
;             PG8_LDB(B0, 0, 0); PG8_LDB(B1, 0, 1); PG8_SCHED; PG8_LDA(At, 0, 0); PG8_STAGE(PG8_SA(1, 1), a1 + hstep, voffA);
;             PG8_WAIT_V(8); PG8_WAIT_L(0); PG8_BAR; PG8_MMA(0, 0, At, B0); PG8_MMA(0, 1, At, B1); PG8_BAR; PG8_SCHED;
;             PG8_LDA(At, 0, 1); PG8_STAGE(PG8_SB(0, 0), b2, voffB); PG8_STAGE(PG8_SB(0, 1), b2 + hstep, voffB); PG8_STAGE(PG8_SA(0, 0), a2, voffA);
;             PG8_WAIT_V(8); PG8_WAIT_L(0); PG8_BAR; PG8_MMA(1, 0, At, B0); PG8_MMA(1, 1, At, B1); PG8_BAR; PG8_SCHED;
;             PG8_LDB(B0, 1, 0); PG8_LDB(B1, 1, 1); PG8_SCHED; PG8_LDA(At, 1, 0); PG8_STAGE(PG8_SA(0, 1), a2 + hstep, voffA);
;             PG8_WAIT_V(8); PG8_WAIT_L(0); PG8_BAR; PG8_MMA(0, 0, At, B0); PG8_MMA(0, 1, At, B1); PG8_BAR; PG8_SCHED;
;             PG8_LDA(At, 1, 1); PG8_STAGE(PG8_SB(1, 0), b3, voffB); PG8_STAGE(PG8_SB(1, 1), b3 + hstep, voffB); PG8_STAGE(PG8_SA(1, 0), a3, voffA);
;             PG8_WAIT_V(8); PG8_WAIT_L(0); PG8_BAR; PG8_MMA(1, 0, At, B0); PG8_MMA(1, 1, At, B1); PG8_BAR; PG8_SCHED;
.LBB0_1135:
	s_add_u32 s18, s4, 0xfffc0080
	s_addc_u32 s19, s5, -1
	s_add_i32 s45, 0, 0x10000
	s_cmp_eq_u32 s44, 12
	s_cselect_b32 s21, s11, s19
	s_cselect_b32 s20, s40, s18
	s_cselect_b32 s19, s13, s43
	s_cselect_b32 s18, s41, s42
	s_add_i32 s48, 0, 0x14000
	v_add_u32_e32 v68, s45, v169
	v_add_u32_e32 v158, s48, v169
	ds_read_b128 v[56:59], v68
	ds_read_b128 v[60:63], v68 offset:1024
	ds_read_b128 v[64:67], v68 offset:2048
	ds_read_b128 v[68:71], v68 offset:3072
	ds_read_b128 v[154:157], v158
	ds_read_b128 v[162:165], v158 offset:1024
	ds_read_b128 v[172:175], v158 offset:2048
	ds_read_b128 v[176:179], v158 offset:3072
	v_lshl_add_u64 v[158:159], s[4:5], 0, v[150:151]
	s_add_i32 m0, s27, 0xc000
	ds_read_b128 v[180:183], v171
	ds_read_b128 v[184:187], v171 offset:1024
	ds_read_b128 v[194:197], v171 offset:2048
	ds_read_b128 v[206:209], v171 offset:3072
	ds_read_b128 v[210:213], v171 offset:4096
	ds_read_b128 v[214:217], v171 offset:5120
	ds_read_b128 v[218:221], v171 offset:6144
	ds_read_b128 v[222:225], v171 offset:7168
	global_load_lds_dwordx4 v[158:159], off
	v_lshl_add_u64 v[158:159], s[4:5], 0, v[152:153]
	s_add_i32 m0, s27, 0xe000
	s_nop 0
	global_load_lds_dwordx4 v[158:159], off
	s_waitcnt vmcnt(8)
	s_waitcnt lgkmcnt(0)
	s_barrier
	s_setprio 1
	s_waitcnt lgkmcnt(0)
	v_mfma_f32_16x16x32_bf16 v[140:143], v[56:59], v[180:183], v[140:143]
	v_mfma_f32_16x16x32_bf16 v[136:139], v[64:67], v[180:183], v[136:139]
	v_mfma_f32_16x16x32_bf16 v[124:127], v[56:59], v[194:197], v[124:127]
	v_mfma_f32_16x16x32_bf16 v[120:123], v[64:67], v[194:197], v[120:123]
	v_mfma_f32_16x16x32_bf16 v[108:111], v[56:59], v[210:213], v[108:111]
	v_mfma_f32_16x16x32_bf16 v[104:107], v[64:67], v[210:213], v[104:107]
	v_mfma_f32_16x16x32_bf16 v[92:95], v[56:59], v[218:221], v[92:95]
	v_mfma_f32_16x16x32_bf16 v[88:91], v[64:67], v[218:221], v[88:91]
	v_mfma_f32_16x16x32_bf16 v[140:143], v[60:63], v[184:187], v[140:143]
	v_mfma_f32_16x16x32_bf16 v[136:139], v[68:71], v[184:187], v[136:139]
	v_mfma_f32_16x16x32_bf16 v[124:127], v[60:63], v[206:209], v[124:127]
	v_mfma_f32_16x16x32_bf16 v[120:123], v[68:71], v[206:209], v[120:123]
	v_mfma_f32_16x16x32_bf16 v[108:111], v[60:63], v[214:217], v[108:111]
	v_mfma_f32_16x16x32_bf16 v[104:107], v[68:71], v[214:217], v[104:107]
	v_mfma_f32_16x16x32_bf16 v[92:95], v[60:63], v[222:225], v[92:95]
	v_mfma_f32_16x16x32_bf16 v[88:91], v[68:71], v[222:225], v[88:91]
	s_setprio 0
	s_setprio 1
	v_mfma_f32_16x16x32_bf16 v[132:135], v[154:157], v[180:183], v[132:135]
	v_mfma_f32_16x16x32_bf16 v[128:131], v[172:175], v[180:183], v[128:131]
	v_mfma_f32_16x16x32_bf16 v[116:119], v[154:157], v[194:197], v[116:119]
	v_mfma_f32_16x16x32_bf16 v[112:115], v[172:175], v[194:197], v[112:115]
	v_mfma_f32_16x16x32_bf16 v[100:103], v[154:157], v[210:213], v[100:103]
	v_mfma_f32_16x16x32_bf16 v[96:99], v[172:175], v[210:213], v[96:99]
	v_mfma_f32_16x16x32_bf16 v[84:87], v[154:157], v[218:221], v[84:87]
	v_mfma_f32_16x16x32_bf16 v[80:83], v[172:175], v[218:221], v[80:83]
	v_mfma_f32_16x16x32_bf16 v[132:135], v[162:165], v[184:187], v[132:135]
	v_mfma_f32_16x16x32_bf16 v[128:131], v[176:179], v[184:187], v[128:131]
	v_mfma_f32_16x16x32_bf16 v[116:119], v[162:165], v[206:209], v[116:119]
	v_mfma_f32_16x16x32_bf16 v[112:115], v[176:179], v[206:209], v[112:115]
	v_mfma_f32_16x16x32_bf16 v[100:103], v[162:165], v[214:217], v[100:103]
	v_mfma_f32_16x16x32_bf16 v[96:99], v[176:179], v[214:217], v[96:99]
	v_mfma_f32_16x16x32_bf16 v[84:87], v[162:165], v[222:225], v[84:87]
	v_mfma_f32_16x16x32_bf16 v[80:83], v[176:179], v[222:225], v[80:83]
	s_setprio 0
	s_barrier
	s_add_i32 s45, s45, s26
	v_lshl_add_u64 v[158:159], s[18:19], 0, v[160:161]
	s_mov_b32 m0, s45
	ds_read_b128 v[180:183], v171 offset:16384
	ds_read_b128 v[184:187], v171 offset:17408
	ds_read_b128 v[194:197], v171 offset:18432
	ds_read_b128 v[206:209], v171 offset:19456
	ds_read_b128 v[210:213], v171 offset:20480
	ds_read_b128 v[214:217], v171 offset:21504
	ds_read_b128 v[218:221], v171 offset:22528
	ds_read_b128 v[222:225], v171 offset:23552
	global_load_lds_dwordx4 v[158:159], off
	s_add_i32 m0, s45, 0x2000
	s_add_u32 s46, s18, 0x40000
	v_lshl_add_u64 v[166:167], s[18:19], 0, v[144:145]
	s_addc_u32 s47, s19, 0
	s_add_i32 s45, s48, s26
	global_load_lds_dwordx4 v[166:167], off
	v_lshl_add_u64 v[188:189], s[46:47], 0, v[160:161]
	s_mov_b32 m0, s45
	v_lshl_add_u64 v[226:227], s[20:21], 0, v[146:147]
	global_load_lds_dwordx4 v[188:189], off
	v_lshl_add_u64 v[188:189], s[46:47], 0, v[144:145]
	s_add_i32 m0, s45, 0x2000
	s_nop 0
	global_load_lds_dwordx4 v[188:189], off
	v_lshl_add_u64 v[188:189], s[20:21], 0, v[148:149]
	s_mov_b32 m0, s27
	s_nop 0
	global_load_lds_dwordx4 v[188:189], off
	s_mov_b32 m0, s28
	s_nop 0
	global_load_lds_dwordx4 v[226:227], off
	s_waitcnt vmcnt(8)
	s_waitcnt lgkmcnt(0)
	s_barrier
; #define PG8_STAGE(bufoff, gbase, voff) do { _Pragma("unroll") for (int _i = 0; _i < 2; ++_i) \
;         __builtin_amdgcn_global_load_lds((const unsigned*)((const char*)(gbase) + (voff)[_i]), (PG8_LAS unsigned*)(lds + (bufoff) + ldsw + _i * 8192), 16, 0, 0); } while (0)
; #define PG8_LDA(dst, b, h) do { _Pragma("unroll") for (int m = 0; m < 4; ++m) _Pragma("unroll") for (int k = 0; k < 2; ++k) dst[m][k] = *(const PG8_LAS bf16x8*)(lds + PG8_SA(b, h) + aoff + m * 2048 + k * 1024); } while (0)
; #define PG8_LDB(dst, b, h) do { _Pragma("unroll") for (int n = 0; n < 2; ++n) _Pragma("unroll") for (int k = 0; k < 2; ++k) dst[n][k] = *(const PG8_LAS bf16x8*)(lds + PG8_SB(b, h) + boff + n * 2048 + k * 1024); } while (0)
; #define PG8_MMA(ai, bj, At, Bt) do { __builtin_amdgcn_s_setprio(1); _Pragma("unroll") for (int m = 0; m < 4; ++m) _Pragma("unroll") for (int n = 0; n < 2; ++n) _Pragma("unroll") for (int k = 0; k < 2; ++k) \
;         acc[ai][bj][m][n] = __builtin_amdgcn_mfma_f32_16x16x32_bf16(Bt[n][k], At[m][k], acc[ai][bj][m][n], 0, 0, 0); __builtin_amdgcn_s_setprio(0); } while (0)
; #define PG8_WAIT_V(n) asm volatile("s_waitcnt vmcnt(" #n ")" ::: "memory")
; template <class Epi, class Sched, bool ALIGN_EPI = false, bool SP2 = false>
; __device__ __forceinline__ void gemm_phase(PG8_LAS unsigned char* lds, const Gemm g, const Sched& S, const Epi& E) {
;     ...
;             PG8_LDB(B0, 0, 0); PG8_LDB(B1, 0, 1); PG8_SCHED; PG8_LDA(At, 0, 0); PG8_STAGE(PG8_SA(1, 1), a1 + hstep, voffA);
;             PG8_WAIT_V(8); PG8_WAIT_L(0); PG8_BAR; PG8_MMA(0, 0, At, B0); PG8_MMA(0, 1, At, B1); PG8_BAR; PG8_SCHED;
;             PG8_LDA(At, 0, 1); PG8_STAGE(PG8_SB(0, 0), b2, voffB); PG8_STAGE(PG8_SB(0, 1), b2 + hstep, voffB); PG8_STAGE(PG8_SA(0, 0), a2, voffA);
;             PG8_WAIT_V(8); PG8_WAIT_L(0); PG8_BAR; PG8_MMA(1, 0, At, B0); PG8_MMA(1, 1, At, B1); PG8_BAR; PG8_SCHED;
;             PG8_LDB(B0, 1, 0); PG8_LDB(B1, 1, 1); PG8_SCHED; PG8_LDA(At, 1, 0); PG8_STAGE(PG8_SA(0, 1), a2 + hstep, voffA);
;             PG8_WAIT_V(8); PG8_WAIT_L(0); PG8_BAR; PG8_MMA(0, 0, At, B0); PG8_MMA(0, 1, At, B1); PG8_BAR; PG8_SCHED;
;             PG8_LDA(At, 1, 1); PG8_STAGE(PG8_SB(1, 0), b3, voffB); PG8_STAGE(PG8_SB(1, 1), b3 + hstep, voffB); PG8_STAGE(PG8_SA(1, 0), a3, voffA);
;             PG8_WAIT_V(8); PG8_WAIT_L(0); PG8_BAR; PG8_MMA(1, 0, At, B0); PG8_MMA(1, 1, At, B1); PG8_BAR; PG8_SCHED;
	s_setprio 1
	s_waitcnt lgkmcnt(0)
	v_mfma_f32_16x16x32_bf16 v[76:79], v[56:59], v[180:183], v[76:79]
	v_mfma_f32_16x16x32_bf16 v[72:75], v[64:67], v[180:183], v[72:75]
	v_mfma_f32_16x16x32_bf16 v[44:47], v[56:59], v[194:197], v[44:47]
	v_mfma_f32_16x16x32_bf16 v[40:43], v[64:67], v[194:197], v[40:43]
	v_mfma_f32_16x16x32_bf16 v[28:31], v[56:59], v[210:213], v[28:31]
	v_mfma_f32_16x16x32_bf16 v[24:27], v[64:67], v[210:213], v[24:27]
	v_mfma_f32_16x16x32_bf16 v[12:15], v[56:59], v[218:221], v[12:15]
	v_mfma_f32_16x16x32_bf16 v[8:11], v[64:67], v[218:221], v[8:11]
	v_mfma_f32_16x16x32_bf16 v[76:79], v[60:63], v[184:187], v[76:79]
	v_mfma_f32_16x16x32_bf16 v[72:75], v[68:71], v[184:187], v[72:75]
	v_mfma_f32_16x16x32_bf16 v[44:47], v[60:63], v[206:209], v[44:47]
	v_mfma_f32_16x16x32_bf16 v[40:43], v[68:71], v[206:209], v[40:43]
	v_mfma_f32_16x16x32_bf16 v[28:31], v[60:63], v[214:217], v[28:31]
	v_mfma_f32_16x16x32_bf16 v[24:27], v[68:71], v[214:217], v[24:27]
	v_mfma_f32_16x16x32_bf16 v[12:15], v[60:63], v[222:225], v[12:15]
	v_mfma_f32_16x16x32_bf16 v[8:11], v[68:71], v[222:225], v[8:11]
	s_setprio 0
	s_setprio 1
	v_mfma_f32_16x16x32_bf16 v[52:55], v[154:157], v[180:183], v[52:55]
	v_mfma_f32_16x16x32_bf16 v[48:51], v[172:175], v[180:183], v[48:51]
	v_mfma_f32_16x16x32_bf16 v[36:39], v[154:157], v[194:197], v[36:39]
	v_mfma_f32_16x16x32_bf16 v[32:35], v[172:175], v[194:197], v[32:35]
	v_mfma_f32_16x16x32_bf16 v[20:23], v[154:157], v[210:213], v[20:23]
	v_mfma_f32_16x16x32_bf16 v[16:19], v[172:175], v[210:213], v[16:19]
	v_mfma_f32_16x16x32_bf16 v[4:7], v[154:157], v[218:221], v[4:7]
	v_mfma_f32_16x16x32_bf16 v[0:3], v[172:175], v[218:221], v[0:3]
	v_mfma_f32_16x16x32_bf16 v[52:55], v[162:165], v[184:187], v[52:55]
	v_mfma_f32_16x16x32_bf16 v[48:51], v[176:179], v[184:187], v[48:51]
	v_mfma_f32_16x16x32_bf16 v[36:39], v[162:165], v[206:209], v[36:39]
	v_mfma_f32_16x16x32_bf16 v[32:35], v[176:179], v[206:209], v[32:35]
	v_mfma_f32_16x16x32_bf16 v[20:23], v[162:165], v[214:217], v[20:23]
	v_mfma_f32_16x16x32_bf16 v[16:19], v[176:179], v[214:217], v[16:19]
	v_mfma_f32_16x16x32_bf16 v[4:7], v[162:165], v[222:225], v[4:7]
	v_mfma_f32_16x16x32_bf16 v[0:3], v[176:179], v[222:225], v[0:3]
	s_setprio 0
	s_barrier
	s_add_i32 s45, 0, 0x18000
	s_add_i32 s46, 0, 0x1c000
	v_add_u32_e32 v68, s45, v169
	v_add_u32_e32 v176, s46, v169
	ds_read_b128 v[56:59], v68
	ds_read_b128 v[60:63], v68 offset:1024
	ds_read_b128 v[64:67], v68 offset:2048
	ds_read_b128 v[68:71], v68 offset:3072
	ds_read_b128 v[154:157], v176
	ds_read_b128 v[162:165], v176 offset:1024
	ds_read_b128 v[172:175], v176 offset:2048
	ds_read_b128 v[176:179], v176 offset:3072
	s_add_u32 s20, s20, 0x40000
	s_addc_u32 s21, s21, 0
	s_mov_b32 m0, s29
	v_lshl_add_u64 v[228:229], s[20:21], 0, v[148:149]
	ds_read_b128 v[180:183], v171 offset:32768
	ds_read_b128 v[184:187], v171 offset:33792
	ds_read_b128 v[194:197], v171 offset:34816
	ds_read_b128 v[206:209], v171 offset:35840
	ds_read_b128 v[210:213], v171 offset:36864
	ds_read_b128 v[214:217], v171 offset:37888
	ds_read_b128 v[218:221], v171 offset:38912
	ds_read_b128 v[222:225], v171 offset:39936
	global_load_lds_dwordx4 v[228:229], off
	v_lshl_add_u64 v[228:229], s[20:21], 0, v[146:147]
	s_mov_b32 m0, s30
	s_nop 0
	global_load_lds_dwordx4 v[228:229], off
	s_waitcnt vmcnt(8)
	s_waitcnt lgkmcnt(0)
	s_barrier
	s_setprio 1
	s_waitcnt lgkmcnt(0)
	v_mfma_f32_16x16x32_bf16 v[140:143], v[56:59], v[180:183], v[140:143]
	v_mfma_f32_16x16x32_bf16 v[136:139], v[64:67], v[180:183], v[136:139]
	v_mfma_f32_16x16x32_bf16 v[124:127], v[56:59], v[194:197], v[124:127]
	v_mfma_f32_16x16x32_bf16 v[120:123], v[64:67], v[194:197], v[120:123]
	v_mfma_f32_16x16x32_bf16 v[108:111], v[56:59], v[210:213], v[108:111]
	v_mfma_f32_16x16x32_bf16 v[104:107], v[64:67], v[210:213], v[104:107]
	v_mfma_f32_16x16x32_bf16 v[92:95], v[56:59], v[218:221], v[92:95]
	v_mfma_f32_16x16x32_bf16 v[88:91], v[64:67], v[218:221], v[88:91]
	v_mfma_f32_16x16x32_bf16 v[140:143], v[60:63], v[184:187], v[140:143]
	v_mfma_f32_16x16x32_bf16 v[136:139], v[68:71], v[184:187], v[136:139]
	v_mfma_f32_16x16x32_bf16 v[124:127], v[60:63], v[206:209], v[124:127]
	v_mfma_f32_16x16x32_bf16 v[120:123], v[68:71], v[206:209], v[120:123]
	v_mfma_f32_16x16x32_bf16 v[108:111], v[60:63], v[214:217], v[108:111]
	v_mfma_f32_16x16x32_bf16 v[104:107], v[68:71], v[214:217], v[104:107]
	v_mfma_f32_16x16x32_bf16 v[92:95], v[60:63], v[222:225], v[92:95]
	v_mfma_f32_16x16x32_bf16 v[88:91], v[68:71], v[222:225], v[88:91]
	s_setprio 0
	s_setprio 1
	v_mfma_f32_16x16x32_bf16 v[132:135], v[154:157], v[180:183], v[132:135]
	v_mfma_f32_16x16x32_bf16 v[128:131], v[172:175], v[180:183], v[128:131]
	v_mfma_f32_16x16x32_bf16 v[116:119], v[154:157], v[194:197], v[116:119]
	v_mfma_f32_16x16x32_bf16 v[112:115], v[172:175], v[194:197], v[112:115]
	v_mfma_f32_16x16x32_bf16 v[100:103], v[154:157], v[210:213], v[100:103]
	v_mfma_f32_16x16x32_bf16 v[96:99], v[172:175], v[210:213], v[96:99]
	v_mfma_f32_16x16x32_bf16 v[84:87], v[154:157], v[218:221], v[84:87]
	v_mfma_f32_16x16x32_bf16 v[80:83], v[172:175], v[218:221], v[80:83]
	v_mfma_f32_16x16x32_bf16 v[132:135], v[162:165], v[184:187], v[132:135]
	v_mfma_f32_16x16x32_bf16 v[128:131], v[176:179], v[184:187], v[128:131]
	v_mfma_f32_16x16x32_bf16 v[116:119], v[162:165], v[206:209], v[116:119]
	v_mfma_f32_16x16x32_bf16 v[112:115], v[176:179], v[206:209], v[112:115]
	v_mfma_f32_16x16x32_bf16 v[100:103], v[162:165], v[214:217], v[100:103]
	v_mfma_f32_16x16x32_bf16 v[96:99], v[176:179], v[214:217], v[96:99]
	v_mfma_f32_16x16x32_bf16 v[84:87], v[162:165], v[222:225], v[84:87]
	v_mfma_f32_16x16x32_bf16 v[80:83], v[176:179], v[222:225], v[80:83]
	s_setprio 0
	s_barrier
; #define PG8_STAGE(bufoff, gbase, voff) do { _Pragma("unroll") for (int _i = 0; _i < 2; ++_i) \
;         __builtin_amdgcn_global_load_lds((const unsigned*)((const char*)(gbase) + (voff)[_i]), (PG8_LAS unsigned*)(lds + (bufoff) + ldsw + _i * 8192), 16, 0, 0); } while (0)
; #define PG8_LDA(dst, b, h) do { _Pragma("unroll") for (int m = 0; m < 4; ++m) _Pragma("unroll") for (int k = 0; k < 2; ++k) dst[m][k] = *(const PG8_LAS bf16x8*)(lds + PG8_SA(b, h) + aoff + m * 2048 + k * 1024); } while (0)
; #define PG8_LDB(dst, b, h) do { _Pragma("unroll") for (int n = 0; n < 2; ++n) _Pragma("unroll") for (int k = 0; k < 2; ++k) dst[n][k] = *(const PG8_LAS bf16x8*)(lds + PG8_SB(b, h) + boff + n * 2048 + k * 1024); } while (0)
; #define PG8_MMA(ai, bj, At, Bt) do { __builtin_amdgcn_s_setprio(1); _Pragma("unroll") for (int m = 0; m < 4; ++m) _Pragma("unroll") for (int n = 0; n < 2; ++n) _Pragma("unroll") for (int k = 0; k < 2; ++k) \
;         acc[ai][bj][m][n] = __builtin_amdgcn_mfma_f32_16x16x32_bf16(Bt[n][k], At[m][k], acc[ai][bj][m][n], 0, 0, 0); __builtin_amdgcn_s_setprio(0); } while (0)
; #define PG8_WAIT_V(n) asm volatile("s_waitcnt vmcnt(" #n ")" ::: "memory")
; template <class Epi, class Sched, bool ALIGN_EPI = false, bool SP2 = false>
; __device__ __forceinline__ void gemm_phase(PG8_LAS unsigned char* lds, const Gemm g, const Sched& S, const Epi& E) {
;     ...
;             PG8_LDB(B0, 0, 0); PG8_LDB(B1, 0, 1); PG8_SCHED; PG8_LDA(At, 0, 0); PG8_STAGE(PG8_SA(1, 1), a1 + hstep, voffA);
;             PG8_WAIT_V(8); PG8_WAIT_L(0); PG8_BAR; PG8_MMA(0, 0, At, B0); PG8_MMA(0, 1, At, B1); PG8_BAR; PG8_SCHED;
;             PG8_LDA(At, 0, 1); PG8_STAGE(PG8_SB(0, 0), b2, voffB); PG8_STAGE(PG8_SB(0, 1), b2 + hstep, voffB); PG8_STAGE(PG8_SA(0, 0), a2, voffA);
;             PG8_WAIT_V(8); PG8_WAIT_L(0); PG8_BAR; PG8_MMA(1, 0, At, B0); PG8_MMA(1, 1, At, B1); PG8_BAR; PG8_SCHED;
;             PG8_LDB(B0, 1, 0); PG8_LDB(B1, 1, 1); PG8_SCHED; PG8_LDA(At, 1, 0); PG8_STAGE(PG8_SA(0, 1), a2 + hstep, voffA);
;             PG8_WAIT_V(8); PG8_WAIT_L(0); PG8_BAR; PG8_MMA(0, 0, At, B0); PG8_MMA(0, 1, At, B1); PG8_BAR; PG8_SCHED;
;             PG8_LDA(At, 1, 1); PG8_STAGE(PG8_SB(1, 0), b3, voffB); PG8_STAGE(PG8_SB(1, 1), b3 + hstep, voffB); PG8_STAGE(PG8_SA(1, 0), a3, voffA);
;             PG8_WAIT_V(8); PG8_WAIT_L(0); PG8_BAR; PG8_MMA(1, 0, At, B0); PG8_MMA(1, 1, At, B1); PG8_BAR; PG8_SCHED;
	s_add_i32 s20, s45, s26
	v_lshl_add_u64 v[158:159], v[158:159], 0, s[38:39]
	s_mov_b32 m0, s20
	ds_read_b128 v[180:183], v171 offset:49152
	ds_read_b128 v[184:187], v171 offset:50176
	ds_read_b128 v[194:197], v171 offset:51200
	ds_read_b128 v[206:209], v171 offset:52224
	ds_read_b128 v[210:213], v171 offset:53248
	ds_read_b128 v[214:217], v171 offset:54272
	ds_read_b128 v[218:221], v171 offset:55296
	ds_read_b128 v[222:225], v171 offset:56320
	global_load_lds_dwordx4 v[158:159], off
	s_add_i32 m0, s20, 0x2000
	s_add_u32 s18, s18, 0x40080
	v_lshl_add_u64 v[158:159], v[166:167], 0, s[38:39]
	s_addc_u32 s19, s19, 0
	s_add_i32 s20, s46, s26
	global_load_lds_dwordx4 v[158:159], off
	v_lshl_add_u64 v[158:159], s[18:19], 0, v[160:161]
	s_mov_b32 m0, s20
	s_nop 0
	global_load_lds_dwordx4 v[158:159], off
	v_lshl_add_u64 v[158:159], s[18:19], 0, v[144:145]
	s_add_i32 m0, s20, 0x2000
	s_nop 0
	global_load_lds_dwordx4 v[158:159], off
	v_lshl_add_u64 v[158:159], v[188:189], 0, s[38:39]
	s_mov_b32 m0, s35
	s_nop 0
	global_load_lds_dwordx4 v[158:159], off
	v_lshl_add_u64 v[158:159], v[226:227], 0, s[38:39]
	s_mov_b32 m0, s36
	s_nop 0
	global_load_lds_dwordx4 v[158:159], off
	s_waitcnt vmcnt(8)
	s_waitcnt lgkmcnt(0)
	s_barrier
	s_setprio 1
	s_waitcnt lgkmcnt(0)
	v_mfma_f32_16x16x32_bf16 v[76:79], v[56:59], v[180:183], v[76:79]
	v_mfma_f32_16x16x32_bf16 v[72:75], v[64:67], v[180:183], v[72:75]
	v_mfma_f32_16x16x32_bf16 v[44:47], v[56:59], v[194:197], v[44:47]
	v_mfma_f32_16x16x32_bf16 v[40:43], v[64:67], v[194:197], v[40:43]
	v_mfma_f32_16x16x32_bf16 v[28:31], v[56:59], v[210:213], v[28:31]
	v_mfma_f32_16x16x32_bf16 v[24:27], v[64:67], v[210:213], v[24:27]
	v_mfma_f32_16x16x32_bf16 v[12:15], v[56:59], v[218:221], v[12:15]
	v_mfma_f32_16x16x32_bf16 v[8:11], v[64:67], v[218:221], v[8:11]
	v_mfma_f32_16x16x32_bf16 v[76:79], v[60:63], v[184:187], v[76:79]
	v_mfma_f32_16x16x32_bf16 v[72:75], v[68:71], v[184:187], v[72:75]
	v_mfma_f32_16x16x32_bf16 v[44:47], v[60:63], v[206:209], v[44:47]
	v_mfma_f32_16x16x32_bf16 v[40:43], v[68:71], v[206:209], v[40:43]
	v_mfma_f32_16x16x32_bf16 v[28:31], v[60:63], v[214:217], v[28:31]
	v_mfma_f32_16x16x32_bf16 v[24:27], v[68:71], v[214:217], v[24:27]
	v_mfma_f32_16x16x32_bf16 v[12:15], v[60:63], v[222:225], v[12:15]
	v_mfma_f32_16x16x32_bf16 v[8:11], v[68:71], v[222:225], v[8:11]
	s_setprio 0
	s_setprio 1
	v_mfma_f32_16x16x32_bf16 v[52:55], v[154:157], v[180:183], v[52:55]
	v_mfma_f32_16x16x32_bf16 v[48:51], v[172:175], v[180:183], v[48:51]
	v_mfma_f32_16x16x32_bf16 v[36:39], v[154:157], v[194:197], v[36:39]
	v_mfma_f32_16x16x32_bf16 v[32:35], v[172:175], v[194:197], v[32:35]
	v_mfma_f32_16x16x32_bf16 v[20:23], v[154:157], v[210:213], v[20:23]
	v_mfma_f32_16x16x32_bf16 v[16:19], v[172:175], v[210:213], v[16:19]
	v_mfma_f32_16x16x32_bf16 v[4:7], v[154:157], v[218:221], v[4:7]
	v_mfma_f32_16x16x32_bf16 v[0:3], v[172:175], v[218:221], v[0:3]
	v_mfma_f32_16x16x32_bf16 v[52:55], v[162:165], v[184:187], v[52:55]
	v_mfma_f32_16x16x32_bf16 v[48:51], v[176:179], v[184:187], v[48:51]
	v_mfma_f32_16x16x32_bf16 v[36:39], v[162:165], v[206:209], v[36:39]
	v_mfma_f32_16x16x32_bf16 v[32:35], v[176:179], v[206:209], v[32:35]
	v_mfma_f32_16x16x32_bf16 v[20:23], v[162:165], v[214:217], v[20:23]
	v_mfma_f32_16x16x32_bf16 v[16:19], v[176:179], v[214:217], v[16:19]
	v_mfma_f32_16x16x32_bf16 v[4:7], v[162:165], v[222:225], v[4:7]
	v_mfma_f32_16x16x32_bf16 v[0:3], v[176:179], v[222:225], v[0:3]
	s_setprio 0
	s_barrier
	s_add_i32 s44, s44, 2
	s_add_u32 s4, s4, 0x100
	s_addc_u32 s5, s5, 0
	s_add_u32 s42, s42, 0x100
	s_addc_u32 s43, s43, 0
	s_cmp_gt_u32 s44, 13
	s_cbranch_scc0 .LBB0_1135
	s_and_b64 vcc, exec, s[6:7]
	s_cbranch_vccz .LBB0_1138
	s_barrier

;     __device__ __forceinline__ void operator()(const f32x4 (&acc)[2][2][4][2], const Unit& u, int wr_, int wc_, int fr_, int fq_) const {
;         int tx = threadIdx.x; asm volatile("" : "+v"(tx));
;         const int fr = tx & 15, fq = (tx >> 4) & 3, wc = (tx >> 6) & 3, wr = tx >> 8;
;         const int b = u.pm >> 5;
;         const int col0 = u.pn * BM + wc * 32 + 8 * fq;
;         const float* gp = gate + (size_t)b * 6144 + col0;
;         f32x4 gv[2][2], sv[2][2];
; #pragma unroll
;         for (int bj = 0; bj < 2; ++bj)
; #pragma unroll
;             for (int n = 0; n < 2; ++n) { gv[bj][n] = *(const f32x4*)(gp + bj * HALF + n * 4);
;                 sv[bj][n] = anext ? *(const f32x4*)(scale_next + (size_t)b * 6144 + col0 + bj * HALF + n * 4) + 1.0f : (f32x4){0.f, 0.f, 0.f, 0.f}; }
.LBB0_1218:
	s_and_b64 vcc, exec, s[12:13]
	s_cbranch_vccnz .Lrg6_fast
	s_branch .Lrg6_fastn

; __device__ __forceinline__ unsigned cvt_pk_bf16(float lo, float hi) { unsigned r; asm volatile("v_cvt_pk_bf16_f32 %0, %1, %2" : "=v"(r) : "v"(lo), "v"(hi)); return r; }
;     __device__ __forceinline__ void operator()(const f32x4 (&acc)[2][2][4][2], const Unit& u, int wr_, int wc_, int fr_, int fq_) const {
;     ...
;         const int b = u.pm >> 5;
;         const int col0 = u.pn * BM + wc * 32 + 8 * fq;
;         const float* gp = gate + (size_t)b * 6144 + col0;
;         f32x4 gv[2][2], sv[2][2];
; #pragma unroll
;         for (int bj = 0; bj < 2; ++bj)
; #pragma unroll
;             for (int n = 0; n < 2; ++n) { gv[bj][n] = *(const f32x4*)(gp + bj * HALF + n * 4);
;                 sv[bj][n] = anext ? *(const f32x4*)(scale_next + (size_t)b * 6144 + col0 + bj * HALF + n * 4) + 1.0f : (f32x4){0.f, 0.f, 0.f, 0.f}; }
; #pragma unroll
;         for (int ai = 0; ai < 2; ++ai)
; #pragma unroll
;             for (int m = 0; m < 4; ++m) { int row = u.pm * BM + ai * HALF + wr * 64 + m * 16 + fr; asm volatile("" : "+v"(row));
;                 const size_t off = (size_t)row * 1024 + col0; float ss = 0.f;
; #pragma unroll
;                 for (int bj = 0; bj < 2; ++bj) { u32x4 w;
; #pragma unroll
;                     for (int n = 0; n < 2; ++n) { const f32x4 xi = *(const f32x4*)(xin + off + bj * HALF + n * 4);
;                         const f32x4 xn = xi + gv[bj][n] * acc[ai][bj][m][n];
;                         *(f32x4*)(xout + off + bj * HALF + n * 4) = xn;
;                         if (anext) { ss += (xn[0] * xn[0] + xn[1] * xn[1]) + (xn[2] * xn[2] + xn[3] * xn[3]);
;                             const f32x4 an = xn * sv[bj][n]; w[2 * n] = cvt_pk_bf16(an[0], an[1]); w[2 * n + 1] = cvt_pk_bf16(an[2], an[3]); } }
;                     if (anext) *(u32x4*)(anext + off + bj * HALF) = w; }
;                 if (anext) { ss += __shfl_xor(ss, 16); ss += __shfl_xor(ss, 32); if (fq == 0) atomicAdd(rss_next + row, ss); }
.Lrg6_fast:
	s_movk_i32 s49, 0x4000
	v_bfe_u32 v227, v190, 4, 2
	v_lshrrev_b32_e32 v144, 1, v190
	v_and_b32_e32 v144, 0x60, v144
	s_lshl_b32 s4, s41, 8
	v_lshlrev_b32_e32 v145, 3, v227
	v_or3_b32 v180, v144, s4, v145
	v_lshlrev_b32_e32 v181, 2, v180
	s_ashr_i32 s4, s33, 5
	s_mul_i32 s4, s4, 0x6000
	s_add_u32 s2, s24, s4
	s_addc_u32 s3, s25, 0
	global_load_dwordx4 v[76:79], v181, s[2:3]
	global_load_dwordx4 v[68:71], v181, s[2:3] offset:16
	global_load_dwordx4 v[60:63], v181, s[2:3] offset:512
	global_load_dwordx4 v[56:59], v181, s[2:3] offset:528
	s_add_u32 s22, s35, s4
	s_addc_u32 s23, s36, 0
	global_load_dwordx4 v[176:179], v181, s[22:23]
	global_load_dwordx4 v[172:175], v181, s[22:23] offset:16
	global_load_dwordx4 v[168:171], v181, s[22:23] offset:512
	global_load_dwordx4 v[164:167], v181, s[22:23] offset:528
	s_lshl_b32 s4, s33, 8
	v_ashrrev_i32_e32 v144, 2, v190
	v_and_b32_e32 v144, 0xffffffc0, v144
	v_and_or_b32 v145, v190, 15, s4
	v_add_u32_e32 v184, v145, v144
	v_lshl_add_u32 v182, v184, 10, v180
	v_lshlrev_b32_e32 v183, 1, v182
	v_lshlrev_b32_e32 v182, 2, v182
	v_lshlrev_b32_e32 v184, 2, v184
	v_mbcnt_lo_u32_b32 v226, -1, 0
	v_mbcnt_hi_u32_b32 v226, -1, v226
	v_xor_b32_e32 v185, 16, v226
	v_lshlrev_b32_e32 v185, 2, v185
	v_xor_b32_e32 v186, 32, v226
	v_lshlrev_b32_e32 v186, 2, v186
	v_cmp_eq_u32_e64 s[4:5], 0, v227
	global_load_dwordx4 v[228:231], v182, s[88:89]
	global_load_dwordx4 v[232:235], v182, s[88:89] offset:16
	global_load_dwordx4 v[236:239], v182, s[88:89] offset:512
	global_load_dwordx4 v[240:243], v182, s[88:89] offset:528
	s_add_u32 s2, s88, 0x10000
	s_addc_u32 s3, s89, 0
	global_load_dwordx4 v[244:247], v182, s[2:3]
	s_add_u32 s2, s88, 0x10000
	s_addc_u32 s3, s89, 0
	global_load_dwordx4 v[248:251], v182, s[2:3] offset:16
	s_add_u32 s2, s88, 0x10000
	s_addc_u32 s3, s89, 0
	global_load_dwordx4 v[208:211], v182, s[2:3] offset:512
	s_add_u32 s2, s88, 0x10000
	s_addc_u32 s3, s89, 0
	global_load_dwordx4 v[212:215], v182, s[2:3] offset:528
	s_waitcnt vmcnt(8)
	v_pk_add_f32 v[176:177], v[176:177], 1.0 op_sel_hi:[1,0]
	v_pk_add_f32 v[178:179], v[178:179], 1.0 op_sel_hi:[1,0]
	v_pk_add_f32 v[172:173], v[172:173], 1.0 op_sel_hi:[1,0]
	v_pk_add_f32 v[174:175], v[174:175], 1.0 op_sel_hi:[1,0]
	v_pk_add_f32 v[168:169], v[168:169], 1.0 op_sel_hi:[1,0]
	v_pk_add_f32 v[170:171], v[170:171], 1.0 op_sel_hi:[1,0]
	v_pk_add_f32 v[164:165], v[164:165], 1.0 op_sel_hi:[1,0]
	v_pk_add_f32 v[166:167], v[166:167], 1.0 op_sel_hi:[1,0]
	s_waitcnt vmcnt(7)
	v_pk_fma_f32 v[64:65], v[64:65], v[76:77], v[228:229]
	v_pk_fma_f32 v[66:67], v[66:67], v[78:79], v[230:231]
	global_store_dwordx4 v182, v[64:67], s[88:89]
	s_add_u32 s2, s88, 0x20000
	s_addc_u32 s3, s89, 0
	global_load_dwordx4 v[228:231], v182, s[2:3]
	v_pk_mul_f32 v[144:145], v[64:65], v[64:65]
	v_pk_mul_f32 v[146:147], v[66:67], v[66:67]
	v_pk_mul_f32 v[220:221], v[176:177], v[64:65]
	v_pk_mul_f32 v[222:223], v[178:179], v[66:67]
	v_add_f32_e32 v144, v144, v145
	v_add_f32_e32 v146, v146, v147
	v_cvt_pk_bf16_f32 v216, v220, v221
	v_cvt_pk_bf16_f32 v217, v222, v223
	v_add_f32_e32 v187, v144, v146
	s_waitcnt vmcnt(8)
	v_pk_fma_f32 v[140:141], v[140:141], v[68:69], v[232:233]
	v_pk_fma_f32 v[142:143], v[142:143], v[70:71], v[234:235]
	global_store_dwordx4 v182, v[140:143], s[88:89] offset:16
	s_add_u32 s2, s88, 0x20000
	s_addc_u32 s3, s89, 0
	global_load_dwordx4 v[232:235], v182, s[2:3] offset:16
	v_pk_mul_f32 v[144:145], v[140:141], v[140:141]
	v_pk_mul_f32 v[146:147], v[142:143], v[142:143]
	v_pk_mul_f32 v[220:221], v[172:173], v[140:141]
	v_pk_mul_f32 v[222:223], v[174:175], v[142:143]
	v_add_f32_e32 v144, v144, v145
	v_add_f32_e32 v146, v146, v147
	v_cvt_pk_bf16_f32 v218, v220, v221
	v_cvt_pk_bf16_f32 v219, v222, v223
	v_add_f32_e32 v144, v144, v146
	v_add_f32_e32 v187, v187, v144
	global_store_dwordx4 v183, v[216:219], s[54:55]
	s_waitcnt vmcnt(10)
	v_pk_fma_f32 v[136:137], v[136:137], v[60:61], v[236:237]
	v_pk_fma_f32 v[138:139], v[138:139], v[62:63], v[238:239]
	global_store_dwordx4 v182, v[136:139], s[88:89] offset:512
	s_add_u32 s2, s88, 0x20000
	s_addc_u32 s3, s89, 0
	global_load_dwordx4 v[236:239], v182, s[2:3] offset:512
	v_pk_mul_f32 v[144:145], v[136:137], v[136:137]
	v_pk_mul_f32 v[146:147], v[138:139], v[138:139]
	v_pk_mul_f32 v[220:221], v[168:169], v[136:137]
	v_pk_mul_f32 v[222:223], v[170:171], v[138:139]
	v_add_f32_e32 v144, v144, v145
	v_add_f32_e32 v146, v146, v147
	v_cvt_pk_bf16_f32 v194, v220, v221
	v_cvt_pk_bf16_f32 v195, v222, v223
	v_add_f32_e32 v144, v144, v146
	v_add_f32_e32 v187, v187, v144
	s_waitcnt vmcnt(11)
	v_pk_fma_f32 v[132:133], v[132:133], v[56:57], v[240:241]
	v_pk_fma_f32 v[134:135], v[134:135], v[58:59], v[242:243]
	global_store_dwordx4 v182, v[132:135], s[88:89] offset:528
	s_add_u32 s2, s88, 0x20000
	s_addc_u32 s3, s89, 0
	global_load_dwordx4 v[240:243], v182, s[2:3] offset:528
	v_pk_mul_f32 v[144:145], v[132:133], v[132:133]
	v_pk_mul_f32 v[146:147], v[134:135], v[134:135]
	v_pk_mul_f32 v[220:221], v[164:165], v[132:133]
	v_pk_mul_f32 v[222:223], v[166:167], v[134:135]
	v_add_f32_e32 v144, v144, v145
	v_add_f32_e32 v146, v146, v147
	v_cvt_pk_bf16_f32 v196, v220, v221
	v_cvt_pk_bf16_f32 v197, v222, v223
	v_add_f32_e32 v144, v144, v146
	v_add_f32_e32 v187, v187, v144
	global_store_dwordx4 v183, v[194:197], s[54:55] offset:256
	ds_bpermute_b32 v225, v185, v187
	s_waitcnt vmcnt(13)
; __device__ __forceinline__ unsigned cvt_pk_bf16(float lo, float hi) { unsigned r; asm volatile("v_cvt_pk_bf16_f32 %0, %1, %2" : "=v"(r) : "v"(lo), "v"(hi)); return r; }
;     __device__ __forceinline__ void operator()(const f32x4 (&acc)[2][2][4][2], const Unit& u, int wr_, int wc_, int fr_, int fq_) const {
;     ...
;             for (int m = 0; m < 4; ++m) { int row = u.pm * BM + ai * HALF + wr * 64 + m * 16 + fr; asm volatile("" : "+v"(row));
;                 const size_t off = (size_t)row * 1024 + col0; float ss = 0.f;
; #pragma unroll
;                 for (int bj = 0; bj < 2; ++bj) { u32x4 w;
; #pragma unroll
;                     for (int n = 0; n < 2; ++n) { const f32x4 xi = *(const f32x4*)(xin + off + bj * HALF + n * 4);
;                         const f32x4 xn = xi + gv[bj][n] * acc[ai][bj][m][n];
;                         *(f32x4*)(xout + off + bj * HALF + n * 4) = xn;
;                         if (anext) { ss += (xn[0] * xn[0] + xn[1] * xn[1]) + (xn[2] * xn[2] + xn[3] * xn[3]);
;                             const f32x4 an = xn * sv[bj][n]; w[2 * n] = cvt_pk_bf16(an[0], an[1]); w[2 * n + 1] = cvt_pk_bf16(an[2], an[3]); } }
;                     if (anext) *(u32x4*)(anext + off + bj * HALF) = w; }
;                 if (anext) { ss += __shfl_xor(ss, 16); ss += __shfl_xor(ss, 32); if (fq == 0) atomicAdd(rss_next + row, ss); }
;                 asm volatile("" ::: "memory"); }
	v_pk_fma_f32 v[128:129], v[128:129], v[76:77], v[244:245]
	v_pk_fma_f32 v[130:131], v[130:131], v[78:79], v[246:247]
	s_add_u32 s22, s88, 0x10000
	s_addc_u32 s23, s89, 0
	global_store_dwordx4 v182, v[128:131], s[22:23]
	s_add_u32 s2, s88, 0x30000
	s_addc_u32 s3, s89, 0
	global_load_dwordx4 v[244:247], v182, s[2:3]
	v_pk_mul_f32 v[144:145], v[128:129], v[128:129]
	v_pk_mul_f32 v[146:147], v[130:131], v[130:131]
	v_pk_mul_f32 v[220:221], v[176:177], v[128:129]
	v_pk_mul_f32 v[222:223], v[178:179], v[130:131]
	v_add_f32_e32 v144, v144, v145
	v_add_f32_e32 v146, v146, v147
	v_cvt_pk_bf16_f32 v216, v220, v221
	v_cvt_pk_bf16_f32 v217, v222, v223
	v_add_f32_e32 v224, v144, v146
	s_waitcnt vmcnt(14)
	v_pk_fma_f32 v[124:125], v[124:125], v[68:69], v[248:249]
	v_pk_fma_f32 v[126:127], v[126:127], v[70:71], v[250:251]
	s_add_u32 s22, s88, 0x10000
	s_addc_u32 s23, s89, 0
	global_store_dwordx4 v182, v[124:127], s[22:23] offset:16
	s_add_u32 s2, s88, 0x30000
	s_addc_u32 s3, s89, 0
	global_load_dwordx4 v[248:251], v182, s[2:3] offset:16
	v_pk_mul_f32 v[144:145], v[124:125], v[124:125]
	v_pk_mul_f32 v[146:147], v[126:127], v[126:127]
	v_pk_mul_f32 v[220:221], v[172:173], v[124:125]
	v_pk_mul_f32 v[222:223], v[174:175], v[126:127]
	v_add_f32_e32 v144, v144, v145
	v_add_f32_e32 v146, v146, v147
	v_cvt_pk_bf16_f32 v218, v220, v221
	v_cvt_pk_bf16_f32 v219, v222, v223
	v_add_f32_e32 v144, v144, v146
	v_add_f32_e32 v224, v224, v144
	s_add_u32 s22, s54, 0x8000
	s_addc_u32 s23, s55, 0
	global_store_dwordx4 v183, v[216:219], s[22:23]
	s_waitcnt lgkmcnt(0)
	v_add_f32_e32 v187, v187, v225
	ds_bpermute_b32 v225, v186, v187
	s_waitcnt vmcnt(16)
	v_pk_fma_f32 v[120:121], v[120:121], v[60:61], v[208:209]
	v_pk_fma_f32 v[122:123], v[122:123], v[62:63], v[210:211]
	s_add_u32 s22, s88, 0x10000
	s_addc_u32 s23, s89, 0
	global_store_dwordx4 v182, v[120:123], s[22:23] offset:512
	s_add_u32 s2, s88, 0x30000
	s_addc_u32 s3, s89, 0
	global_load_dwordx4 v[208:211], v182, s[2:3] offset:512
	v_pk_mul_f32 v[144:145], v[120:121], v[120:121]
	v_pk_mul_f32 v[146:147], v[122:123], v[122:123]
	v_pk_mul_f32 v[220:221], v[168:169], v[120:121]
	v_pk_mul_f32 v[222:223], v[170:171], v[122:123]
	v_add_f32_e32 v144, v144, v145
	v_add_f32_e32 v146, v146, v147
	v_cvt_pk_bf16_f32 v194, v220, v221
	v_cvt_pk_bf16_f32 v195, v222, v223
	v_add_f32_e32 v144, v144, v146
	v_add_f32_e32 v224, v224, v144
	s_waitcnt lgkmcnt(0)
	v_add_f32_e32 v225, v187, v225
	s_and_saveexec_b64 vcc, s[4:5]
	global_atomic_add_f32 v184, v225, s[8:9]
	s_mov_b64 exec, vcc
	s_waitcnt vmcnt(18)
	v_pk_fma_f32 v[116:117], v[116:117], v[56:57], v[212:213]
	v_pk_fma_f32 v[118:119], v[118:119], v[58:59], v[214:215]
	s_add_u32 s22, s88, 0x10000
	s_addc_u32 s23, s89, 0
	global_store_dwordx4 v182, v[116:119], s[22:23] offset:528
	s_add_u32 s2, s88, 0x30000
	s_addc_u32 s3, s89, 0
	global_load_dwordx4 v[212:215], v182, s[2:3] offset:528
	v_pk_mul_f32 v[144:145], v[116:117], v[116:117]
	v_pk_mul_f32 v[146:147], v[118:119], v[118:119]
	v_pk_mul_f32 v[220:221], v[164:165], v[116:117]
	v_pk_mul_f32 v[222:223], v[166:167], v[118:119]
	v_add_f32_e32 v144, v144, v145
	v_add_f32_e32 v146, v146, v147
	v_cvt_pk_bf16_f32 v196, v220, v221
	v_cvt_pk_bf16_f32 v197, v222, v223
	v_add_f32_e32 v144, v144, v146
	v_add_f32_e32 v224, v224, v144
	s_add_u32 s22, s54, 0x8000
	s_addc_u32 s23, s55, 0
	global_store_dwordx4 v183, v[194:197], s[22:23] offset:256
	ds_bpermute_b32 v225, v185, v224
	s_waitcnt vmcnt(19)
	v_pk_fma_f32 v[112:113], v[112:113], v[76:77], v[228:229]
	v_pk_fma_f32 v[114:115], v[114:115], v[78:79], v[230:231]
	s_add_u32 s22, s88, 0x20000
	s_addc_u32 s23, s89, 0
	global_store_dwordx4 v182, v[112:115], s[22:23]
	s_add_u32 s2, s88, 0x80000
	s_addc_u32 s3, s89, 0
	global_load_dwordx4 v[228:231], v182, s[2:3]
	v_pk_mul_f32 v[144:145], v[112:113], v[112:113]
	v_pk_mul_f32 v[146:147], v[114:115], v[114:115]
	v_pk_mul_f32 v[220:221], v[176:177], v[112:113]
	v_pk_mul_f32 v[222:223], v[178:179], v[114:115]
	v_add_f32_e32 v144, v144, v145
	v_add_f32_e32 v146, v146, v147
	v_cvt_pk_bf16_f32 v216, v220, v221
	v_cvt_pk_bf16_f32 v217, v222, v223
	v_add_f32_e32 v187, v144, v146
	s_waitcnt vmcnt(19)
	v_pk_fma_f32 v[108:109], v[108:109], v[68:69], v[232:233]
	v_pk_fma_f32 v[110:111], v[110:111], v[70:71], v[234:235]
	s_add_u32 s22, s88, 0x20000
	s_addc_u32 s23, s89, 0
	global_store_dwordx4 v182, v[108:111], s[22:23] offset:16
	s_add_u32 s2, s88, 0x80000
	s_addc_u32 s3, s89, 0
	global_load_dwordx4 v[232:235], v182, s[2:3] offset:16
	v_pk_mul_f32 v[144:145], v[108:109], v[108:109]
	v_pk_mul_f32 v[146:147], v[110:111], v[110:111]
	v_pk_mul_f32 v[220:221], v[172:173], v[108:109]
	v_pk_mul_f32 v[222:223], v[174:175], v[110:111]
	v_add_f32_e32 v144, v144, v145
	v_add_f32_e32 v146, v146, v147
	v_cvt_pk_bf16_f32 v218, v220, v221
	v_cvt_pk_bf16_f32 v219, v222, v223
	v_add_f32_e32 v144, v144, v146
	v_add_f32_e32 v187, v187, v144
	s_add_u32 s22, s54, 0x10000
	s_addc_u32 s23, s55, 0
	global_store_dwordx4 v183, v[216:219], s[22:23]
	s_waitcnt lgkmcnt(0)
	v_add_f32_e32 v224, v224, v225
	ds_bpermute_b32 v225, v186, v224
	s_waitcnt vmcnt(19)
	v_pk_fma_f32 v[104:105], v[104:105], v[60:61], v[236:237]
	v_pk_fma_f32 v[106:107], v[106:107], v[62:63], v[238:239]
	s_add_u32 s22, s88, 0x20000
	s_addc_u32 s23, s89, 0
	global_store_dwordx4 v182, v[104:107], s[22:23] offset:512
	s_add_u32 s2, s88, 0x80000
	s_addc_u32 s3, s89, 0
	global_load_dwordx4 v[236:239], v182, s[2:3] offset:512
	v_pk_mul_f32 v[144:145], v[104:105], v[104:105]
	v_pk_mul_f32 v[146:147], v[106:107], v[106:107]
	v_pk_mul_f32 v[220:221], v[168:169], v[104:105]
	v_pk_mul_f32 v[222:223], v[170:171], v[106:107]
	v_add_f32_e32 v144, v144, v145
	v_add_f32_e32 v146, v146, v147
	v_cvt_pk_bf16_f32 v194, v220, v221
	v_cvt_pk_bf16_f32 v195, v222, v223
	v_add_f32_e32 v144, v144, v146
	v_add_f32_e32 v187, v187, v144
	s_waitcnt lgkmcnt(0)
; __device__ __forceinline__ unsigned cvt_pk_bf16(float lo, float hi) { unsigned r; asm volatile("v_cvt_pk_bf16_f32 %0, %1, %2" : "=v"(r) : "v"(lo), "v"(hi)); return r; }
;     __device__ __forceinline__ void operator()(const f32x4 (&acc)[2][2][4][2], const Unit& u, int wr_, int wc_, int fr_, int fq_) const {
;     ...
;             for (int m = 0; m < 4; ++m) { int row = u.pm * BM + ai * HALF + wr * 64 + m * 16 + fr; asm volatile("" : "+v"(row));
;                 const size_t off = (size_t)row * 1024 + col0; float ss = 0.f;
; #pragma unroll
;                 for (int bj = 0; bj < 2; ++bj) { u32x4 w;
; #pragma unroll
;                     for (int n = 0; n < 2; ++n) { const f32x4 xi = *(const f32x4*)(xin + off + bj * HALF + n * 4);
;                         const f32x4 xn = xi + gv[bj][n] * acc[ai][bj][m][n];
;                         *(f32x4*)(xout + off + bj * HALF + n * 4) = xn;
;                         if (anext) { ss += (xn[0] * xn[0] + xn[1] * xn[1]) + (xn[2] * xn[2] + xn[3] * xn[3]);
;                             const f32x4 an = xn * sv[bj][n]; w[2 * n] = cvt_pk_bf16(an[0], an[1]); w[2 * n + 1] = cvt_pk_bf16(an[2], an[3]); } }
;                     if (anext) *(u32x4*)(anext + off + bj * HALF) = w; }
;                 if (anext) { ss += __shfl_xor(ss, 16); ss += __shfl_xor(ss, 32); if (fq == 0) atomicAdd(rss_next + row, ss); }
;                 asm volatile("" ::: "memory"); }
	v_add_f32_e32 v225, v224, v225
	s_and_saveexec_b64 vcc, s[4:5]
	global_atomic_add_f32 v184, v225, s[8:9] offset:64
	s_mov_b64 exec, vcc
	s_waitcnt vmcnt(20)
	v_pk_fma_f32 v[100:101], v[100:101], v[56:57], v[240:241]
	v_pk_fma_f32 v[102:103], v[102:103], v[58:59], v[242:243]
	s_add_u32 s22, s88, 0x20000
	s_addc_u32 s23, s89, 0
	global_store_dwordx4 v182, v[100:103], s[22:23] offset:528
	s_add_u32 s2, s88, 0x80000
	s_addc_u32 s3, s89, 0
	global_load_dwordx4 v[240:243], v182, s[2:3] offset:528
	v_pk_mul_f32 v[144:145], v[100:101], v[100:101]
	v_pk_mul_f32 v[146:147], v[102:103], v[102:103]
	v_pk_mul_f32 v[220:221], v[164:165], v[100:101]
	v_pk_mul_f32 v[222:223], v[166:167], v[102:103]
	v_add_f32_e32 v144, v144, v145
	v_add_f32_e32 v146, v146, v147
	v_cvt_pk_bf16_f32 v196, v220, v221
	v_cvt_pk_bf16_f32 v197, v222, v223
	v_add_f32_e32 v144, v144, v146
	v_add_f32_e32 v187, v187, v144
	s_add_u32 s22, s54, 0x10000
	s_addc_u32 s23, s55, 0
	global_store_dwordx4 v183, v[194:197], s[22:23] offset:256
	ds_bpermute_b32 v225, v185, v187
	s_waitcnt vmcnt(20)
	v_pk_fma_f32 v[96:97], v[96:97], v[76:77], v[244:245]
	v_pk_fma_f32 v[98:99], v[98:99], v[78:79], v[246:247]
	s_add_u32 s22, s88, 0x30000
	s_addc_u32 s23, s89, 0
	global_store_dwordx4 v182, v[96:99], s[22:23]
	s_add_u32 s2, s88, 0x90000
	s_addc_u32 s3, s89, 0
	global_load_dwordx4 v[244:247], v182, s[2:3]
	v_pk_mul_f32 v[144:145], v[96:97], v[96:97]
	v_pk_mul_f32 v[146:147], v[98:99], v[98:99]
	v_pk_mul_f32 v[220:221], v[176:177], v[96:97]
	v_pk_mul_f32 v[222:223], v[178:179], v[98:99]
	v_add_f32_e32 v144, v144, v145
	v_add_f32_e32 v146, v146, v147
	v_cvt_pk_bf16_f32 v216, v220, v221
	v_cvt_pk_bf16_f32 v217, v222, v223
	v_add_f32_e32 v224, v144, v146
	s_waitcnt vmcnt(20)
	v_pk_fma_f32 v[92:93], v[92:93], v[68:69], v[248:249]
	v_pk_fma_f32 v[94:95], v[94:95], v[70:71], v[250:251]
	s_add_u32 s22, s88, 0x30000
	s_addc_u32 s23, s89, 0
	global_store_dwordx4 v182, v[92:95], s[22:23] offset:16
	s_add_u32 s2, s88, 0x90000
	s_addc_u32 s3, s89, 0
	global_load_dwordx4 v[248:251], v182, s[2:3] offset:16
	v_pk_mul_f32 v[144:145], v[92:93], v[92:93]
	v_pk_mul_f32 v[146:147], v[94:95], v[94:95]
	v_pk_mul_f32 v[220:221], v[172:173], v[92:93]
	v_pk_mul_f32 v[222:223], v[174:175], v[94:95]
	v_add_f32_e32 v144, v144, v145
	v_add_f32_e32 v146, v146, v147
	v_cvt_pk_bf16_f32 v218, v220, v221
	v_cvt_pk_bf16_f32 v219, v222, v223
	v_add_f32_e32 v144, v144, v146
	v_add_f32_e32 v224, v224, v144
	s_add_u32 s22, s54, 0x18000
	s_addc_u32 s23, s55, 0
	global_store_dwordx4 v183, v[216:219], s[22:23]
	s_waitcnt lgkmcnt(0)
	v_add_f32_e32 v187, v187, v225
	ds_bpermute_b32 v225, v186, v187
	s_waitcnt vmcnt(20)
	v_pk_fma_f32 v[88:89], v[88:89], v[60:61], v[208:209]
	v_pk_fma_f32 v[90:91], v[90:91], v[62:63], v[210:211]
	s_add_u32 s22, s88, 0x30000
	s_addc_u32 s23, s89, 0
	global_store_dwordx4 v182, v[88:91], s[22:23] offset:512
	s_add_u32 s2, s88, 0x90000
	s_addc_u32 s3, s89, 0
	global_load_dwordx4 v[208:211], v182, s[2:3] offset:512
	v_pk_mul_f32 v[144:145], v[88:89], v[88:89]
	v_pk_mul_f32 v[146:147], v[90:91], v[90:91]
	v_pk_mul_f32 v[220:221], v[168:169], v[88:89]
	v_pk_mul_f32 v[222:223], v[170:171], v[90:91]
	v_add_f32_e32 v144, v144, v145
	v_add_f32_e32 v146, v146, v147
	v_cvt_pk_bf16_f32 v194, v220, v221
	v_cvt_pk_bf16_f32 v195, v222, v223
	v_add_f32_e32 v144, v144, v146
	v_add_f32_e32 v224, v224, v144
	s_waitcnt lgkmcnt(0)
	v_add_f32_e32 v225, v187, v225
	s_and_saveexec_b64 vcc, s[4:5]
	global_atomic_add_f32 v184, v225, s[8:9] offset:128
	s_mov_b64 exec, vcc
	s_waitcnt vmcnt(20)
	v_pk_fma_f32 v[84:85], v[84:85], v[56:57], v[212:213]
	v_pk_fma_f32 v[86:87], v[86:87], v[58:59], v[214:215]
	s_add_u32 s22, s88, 0x30000
	s_addc_u32 s23, s89, 0
	global_store_dwordx4 v182, v[84:87], s[22:23] offset:528
	s_add_u32 s2, s88, 0x90000
	s_addc_u32 s3, s89, 0
	global_load_dwordx4 v[212:215], v182, s[2:3] offset:528
	v_pk_mul_f32 v[144:145], v[84:85], v[84:85]
	v_pk_mul_f32 v[146:147], v[86:87], v[86:87]
	v_pk_mul_f32 v[220:221], v[164:165], v[84:85]
	v_pk_mul_f32 v[222:223], v[166:167], v[86:87]
	v_add_f32_e32 v144, v144, v145
	v_add_f32_e32 v146, v146, v147
	v_cvt_pk_bf16_f32 v196, v220, v221
	v_cvt_pk_bf16_f32 v197, v222, v223
	v_add_f32_e32 v144, v144, v146
	v_add_f32_e32 v224, v224, v144
	s_add_u32 s22, s54, 0x18000
	s_addc_u32 s23, s55, 0
	global_store_dwordx4 v183, v[194:197], s[22:23] offset:256
	ds_bpermute_b32 v225, v185, v224
	s_waitcnt vmcnt(20)
	v_pk_fma_f32 v[80:81], v[80:81], v[76:77], v[228:229]
	v_pk_fma_f32 v[82:83], v[82:83], v[78:79], v[230:231]
	s_add_u32 s22, s88, 0x80000
	s_addc_u32 s23, s89, 0
	global_store_dwordx4 v182, v[80:83], s[22:23]
	s_add_u32 s2, s88, 0xa0000
	s_addc_u32 s3, s89, 0
	global_load_dwordx4 v[228:231], v182, s[2:3]
	v_pk_mul_f32 v[144:145], v[80:81], v[80:81]
	v_pk_mul_f32 v[146:147], v[82:83], v[82:83]
	v_pk_mul_f32 v[220:221], v[176:177], v[80:81]
	v_pk_mul_f32 v[222:223], v[178:179], v[82:83]
	v_add_f32_e32 v144, v144, v145
	v_add_f32_e32 v146, v146, v147
	v_cvt_pk_bf16_f32 v216, v220, v221
	v_cvt_pk_bf16_f32 v217, v222, v223
	v_add_f32_e32 v187, v144, v146
	s_waitcnt vmcnt(20)
	v_pk_fma_f32 v[72:73], v[72:73], v[68:69], v[232:233]
	v_pk_fma_f32 v[74:75], v[74:75], v[70:71], v[234:235]
	s_add_u32 s22, s88, 0x80000
	s_addc_u32 s23, s89, 0
	global_store_dwordx4 v182, v[72:75], s[22:23] offset:16
	s_add_u32 s2, s88, 0xa0000
	s_addc_u32 s3, s89, 0
	global_load_dwordx4 v[232:235], v182, s[2:3] offset:16
	v_pk_mul_f32 v[144:145], v[72:73], v[72:73]
	v_pk_mul_f32 v[146:147], v[74:75], v[74:75]
	v_pk_mul_f32 v[220:221], v[172:173], v[72:73]
	v_pk_mul_f32 v[222:223], v[174:175], v[74:75]
	v_add_f32_e32 v144, v144, v145
	v_add_f32_e32 v146, v146, v147
	v_cvt_pk_bf16_f32 v218, v220, v221
	v_cvt_pk_bf16_f32 v219, v222, v223
	v_add_f32_e32 v144, v144, v146
	v_add_f32_e32 v187, v187, v144
	s_add_u32 s22, s54, 0x40000
	s_addc_u32 s23, s55, 0
	global_store_dwordx4 v183, v[216:219], s[22:23]
	s_waitcnt lgkmcnt(0)
; __device__ __forceinline__ unsigned cvt_pk_bf16(float lo, float hi) { unsigned r; asm volatile("v_cvt_pk_bf16_f32 %0, %1, %2" : "=v"(r) : "v"(lo), "v"(hi)); return r; }
;     __device__ __forceinline__ void operator()(const f32x4 (&acc)[2][2][4][2], const Unit& u, int wr_, int wc_, int fr_, int fq_) const {
;     ...
;             for (int m = 0; m < 4; ++m) { int row = u.pm * BM + ai * HALF + wr * 64 + m * 16 + fr; asm volatile("" : "+v"(row));
;                 const size_t off = (size_t)row * 1024 + col0; float ss = 0.f;
; #pragma unroll
;                 for (int bj = 0; bj < 2; ++bj) { u32x4 w;
; #pragma unroll
;                     for (int n = 0; n < 2; ++n) { const f32x4 xi = *(const f32x4*)(xin + off + bj * HALF + n * 4);
;                         const f32x4 xn = xi + gv[bj][n] * acc[ai][bj][m][n];
;                         *(f32x4*)(xout + off + bj * HALF + n * 4) = xn;
;                         if (anext) { ss += (xn[0] * xn[0] + xn[1] * xn[1]) + (xn[2] * xn[2] + xn[3] * xn[3]);
;                             const f32x4 an = xn * sv[bj][n]; w[2 * n] = cvt_pk_bf16(an[0], an[1]); w[2 * n + 1] = cvt_pk_bf16(an[2], an[3]); } }
;                     if (anext) *(u32x4*)(anext + off + bj * HALF) = w; }
;                 if (anext) { ss += __shfl_xor(ss, 16); ss += __shfl_xor(ss, 32); if (fq == 0) atomicAdd(rss_next + row, ss); }
;                 asm volatile("" ::: "memory"); }
	v_add_f32_e32 v224, v224, v225
	ds_bpermute_b32 v225, v186, v224
	s_waitcnt vmcnt(20)
	v_pk_fma_f32 v[52:53], v[52:53], v[60:61], v[236:237]
	v_pk_fma_f32 v[54:55], v[54:55], v[62:63], v[238:239]
	s_add_u32 s22, s88, 0x80000
	s_addc_u32 s23, s89, 0
	global_store_dwordx4 v182, v[52:55], s[22:23] offset:512
	s_add_u32 s2, s88, 0xa0000
	s_addc_u32 s3, s89, 0
	global_load_dwordx4 v[236:239], v182, s[2:3] offset:512
	v_pk_mul_f32 v[144:145], v[52:53], v[52:53]
	v_pk_mul_f32 v[146:147], v[54:55], v[54:55]
	v_pk_mul_f32 v[220:221], v[168:169], v[52:53]
	v_pk_mul_f32 v[222:223], v[170:171], v[54:55]
	v_add_f32_e32 v144, v144, v145
	v_add_f32_e32 v146, v146, v147
	v_cvt_pk_bf16_f32 v194, v220, v221
	v_cvt_pk_bf16_f32 v195, v222, v223
	v_add_f32_e32 v144, v144, v146
	v_add_f32_e32 v187, v187, v144
	s_waitcnt lgkmcnt(0)
	v_add_f32_e32 v225, v224, v225
	s_and_saveexec_b64 vcc, s[4:5]
	global_atomic_add_f32 v184, v225, s[8:9] offset:192
	s_mov_b64 exec, vcc
	s_waitcnt vmcnt(20)
	v_pk_fma_f32 v[48:49], v[48:49], v[56:57], v[240:241]
	v_pk_fma_f32 v[50:51], v[50:51], v[58:59], v[242:243]
	s_add_u32 s22, s88, 0x80000
	s_addc_u32 s23, s89, 0
	global_store_dwordx4 v182, v[48:51], s[22:23] offset:528
	s_add_u32 s2, s88, 0xa0000
	s_addc_u32 s3, s89, 0
	global_load_dwordx4 v[240:243], v182, s[2:3] offset:528
	v_pk_mul_f32 v[144:145], v[48:49], v[48:49]
	v_pk_mul_f32 v[146:147], v[50:51], v[50:51]
	v_pk_mul_f32 v[220:221], v[164:165], v[48:49]
	v_pk_mul_f32 v[222:223], v[166:167], v[50:51]
	v_add_f32_e32 v144, v144, v145
	v_add_f32_e32 v146, v146, v147
	v_cvt_pk_bf16_f32 v196, v220, v221
	v_cvt_pk_bf16_f32 v197, v222, v223
	v_add_f32_e32 v144, v144, v146
	v_add_f32_e32 v187, v187, v144
	s_add_u32 s22, s54, 0x40000
	s_addc_u32 s23, s55, 0
	global_store_dwordx4 v183, v[194:197], s[22:23] offset:256
	ds_bpermute_b32 v225, v185, v187
	s_waitcnt vmcnt(20)
	v_pk_fma_f32 v[44:45], v[44:45], v[76:77], v[244:245]
	v_pk_fma_f32 v[46:47], v[46:47], v[78:79], v[246:247]
	s_add_u32 s22, s88, 0x90000
	s_addc_u32 s23, s89, 0
	global_store_dwordx4 v182, v[44:47], s[22:23]
	s_add_u32 s2, s88, 0xb0000
	s_addc_u32 s3, s89, 0
	global_load_dwordx4 v[244:247], v182, s[2:3]
	v_pk_mul_f32 v[144:145], v[44:45], v[44:45]
	v_pk_mul_f32 v[146:147], v[46:47], v[46:47]
	v_pk_mul_f32 v[220:221], v[176:177], v[44:45]
	v_pk_mul_f32 v[222:223], v[178:179], v[46:47]
	v_add_f32_e32 v144, v144, v145
	v_add_f32_e32 v146, v146, v147
	v_cvt_pk_bf16_f32 v216, v220, v221
	v_cvt_pk_bf16_f32 v217, v222, v223
	v_add_f32_e32 v224, v144, v146
	s_waitcnt vmcnt(20)
	v_pk_fma_f32 v[40:41], v[40:41], v[68:69], v[248:249]
	v_pk_fma_f32 v[42:43], v[42:43], v[70:71], v[250:251]
	s_add_u32 s22, s88, 0x90000
	s_addc_u32 s23, s89, 0
	global_store_dwordx4 v182, v[40:43], s[22:23] offset:16
	s_add_u32 s2, s88, 0xb0000
	s_addc_u32 s3, s89, 0
	global_load_dwordx4 v[248:251], v182, s[2:3] offset:16
	v_pk_mul_f32 v[144:145], v[40:41], v[40:41]
	v_pk_mul_f32 v[146:147], v[42:43], v[42:43]
	v_pk_mul_f32 v[220:221], v[172:173], v[40:41]
	v_pk_mul_f32 v[222:223], v[174:175], v[42:43]
	v_add_f32_e32 v144, v144, v145
	v_add_f32_e32 v146, v146, v147
	v_cvt_pk_bf16_f32 v218, v220, v221
	v_cvt_pk_bf16_f32 v219, v222, v223
	v_add_f32_e32 v144, v144, v146
	v_add_f32_e32 v224, v224, v144
	s_add_u32 s22, s54, 0x48000
	s_addc_u32 s23, s55, 0
	global_store_dwordx4 v183, v[216:219], s[22:23]
	s_waitcnt lgkmcnt(0)
	v_add_f32_e32 v187, v187, v225
	ds_bpermute_b32 v225, v186, v187
	s_waitcnt vmcnt(20)
	v_pk_fma_f32 v[36:37], v[36:37], v[60:61], v[208:209]
	v_pk_fma_f32 v[38:39], v[38:39], v[62:63], v[210:211]
	s_add_u32 s22, s88, 0x90000
	s_addc_u32 s23, s89, 0
	global_store_dwordx4 v182, v[36:39], s[22:23] offset:512
	s_add_u32 s2, s88, 0xb0000
	s_addc_u32 s3, s89, 0
	global_load_dwordx4 v[208:211], v182, s[2:3] offset:512
	v_pk_mul_f32 v[144:145], v[36:37], v[36:37]
	v_pk_mul_f32 v[146:147], v[38:39], v[38:39]
	v_pk_mul_f32 v[220:221], v[168:169], v[36:37]
	v_pk_mul_f32 v[222:223], v[170:171], v[38:39]
	v_add_f32_e32 v144, v144, v145
	v_add_f32_e32 v146, v146, v147
	v_cvt_pk_bf16_f32 v194, v220, v221
	v_cvt_pk_bf16_f32 v195, v222, v223
	v_add_f32_e32 v144, v144, v146
	v_add_f32_e32 v224, v224, v144
	s_waitcnt lgkmcnt(0)
	v_add_f32_e32 v225, v187, v225
	s_and_saveexec_b64 vcc, s[4:5]
	global_atomic_add_f32 v184, v225, s[8:9] offset:512
	s_mov_b64 exec, vcc
	s_waitcnt vmcnt(20)
	v_pk_fma_f32 v[32:33], v[32:33], v[56:57], v[212:213]
	v_pk_fma_f32 v[34:35], v[34:35], v[58:59], v[214:215]
	s_add_u32 s22, s88, 0x90000
	s_addc_u32 s23, s89, 0
	global_store_dwordx4 v182, v[32:35], s[22:23] offset:528
	s_add_u32 s2, s88, 0xb0000
	s_addc_u32 s3, s89, 0
	global_load_dwordx4 v[212:215], v182, s[2:3] offset:528
	v_pk_mul_f32 v[144:145], v[32:33], v[32:33]
	v_pk_mul_f32 v[146:147], v[34:35], v[34:35]
	v_pk_mul_f32 v[220:221], v[164:165], v[32:33]
	v_pk_mul_f32 v[222:223], v[166:167], v[34:35]
	v_add_f32_e32 v144, v144, v145
	v_add_f32_e32 v146, v146, v147
	v_cvt_pk_bf16_f32 v196, v220, v221
	v_cvt_pk_bf16_f32 v197, v222, v223
	v_add_f32_e32 v144, v144, v146
	v_add_f32_e32 v224, v224, v144
	s_add_u32 s22, s54, 0x48000
	s_addc_u32 s23, s55, 0
	global_store_dwordx4 v183, v[194:197], s[22:23] offset:256
	ds_bpermute_b32 v225, v185, v224
	s_waitcnt vmcnt(20)
	v_pk_fma_f32 v[28:29], v[28:29], v[76:77], v[228:229]
	v_pk_fma_f32 v[30:31], v[30:31], v[78:79], v[230:231]
	s_add_u32 s22, s88, 0xa0000
	s_addc_u32 s23, s89, 0
	global_store_dwordx4 v182, v[28:31], s[22:23]
	v_pk_mul_f32 v[144:145], v[28:29], v[28:29]
	v_pk_mul_f32 v[146:147], v[30:31], v[30:31]
	v_pk_mul_f32 v[220:221], v[176:177], v[28:29]
	v_pk_mul_f32 v[222:223], v[178:179], v[30:31]
	v_add_f32_e32 v144, v144, v145
	v_add_f32_e32 v146, v146, v147
	v_cvt_pk_bf16_f32 v216, v220, v221
	v_cvt_pk_bf16_f32 v217, v222, v223
	v_add_f32_e32 v187, v144, v146
	s_waitcnt vmcnt(19)
; __device__ __forceinline__ unsigned cvt_pk_bf16(float lo, float hi) { unsigned r; asm volatile("v_cvt_pk_bf16_f32 %0, %1, %2" : "=v"(r) : "v"(lo), "v"(hi)); return r; }
;     __device__ __forceinline__ void operator()(const f32x4 (&acc)[2][2][4][2], const Unit& u, int wr_, int wc_, int fr_, int fq_) const {
;     ...
;             for (int m = 0; m < 4; ++m) { int row = u.pm * BM + ai * HALF + wr * 64 + m * 16 + fr; asm volatile("" : "+v"(row));
;                 const size_t off = (size_t)row * 1024 + col0; float ss = 0.f;
; #pragma unroll
;                 for (int bj = 0; bj < 2; ++bj) { u32x4 w;
; #pragma unroll
;                     for (int n = 0; n < 2; ++n) { const f32x4 xi = *(const f32x4*)(xin + off + bj * HALF + n * 4);
;                         const f32x4 xn = xi + gv[bj][n] * acc[ai][bj][m][n];
;                         *(f32x4*)(xout + off + bj * HALF + n * 4) = xn;
;                         if (anext) { ss += (xn[0] * xn[0] + xn[1] * xn[1]) + (xn[2] * xn[2] + xn[3] * xn[3]);
;                             const f32x4 an = xn * sv[bj][n]; w[2 * n] = cvt_pk_bf16(an[0], an[1]); w[2 * n + 1] = cvt_pk_bf16(an[2], an[3]); } }
;                     if (anext) *(u32x4*)(anext + off + bj * HALF) = w; }
;                 if (anext) { ss += __shfl_xor(ss, 16); ss += __shfl_xor(ss, 32); if (fq == 0) atomicAdd(rss_next + row, ss); }
;                 asm volatile("" ::: "memory"); }
	v_pk_fma_f32 v[24:25], v[24:25], v[68:69], v[232:233]
	v_pk_fma_f32 v[26:27], v[26:27], v[70:71], v[234:235]
	s_add_u32 s22, s88, 0xa0000
	s_addc_u32 s23, s89, 0
	global_store_dwordx4 v182, v[24:27], s[22:23] offset:16
	v_pk_mul_f32 v[144:145], v[24:25], v[24:25]
	v_pk_mul_f32 v[146:147], v[26:27], v[26:27]
	v_pk_mul_f32 v[220:221], v[172:173], v[24:25]
	v_pk_mul_f32 v[222:223], v[174:175], v[26:27]
	v_add_f32_e32 v144, v144, v145
	v_add_f32_e32 v146, v146, v147
	v_cvt_pk_bf16_f32 v218, v220, v221
	v_cvt_pk_bf16_f32 v219, v222, v223
	v_add_f32_e32 v144, v144, v146
	v_add_f32_e32 v187, v187, v144
	s_add_u32 s22, s54, 0x50000
	s_addc_u32 s23, s55, 0
	global_store_dwordx4 v183, v[216:219], s[22:23]
	s_waitcnt lgkmcnt(0)
	v_add_f32_e32 v224, v224, v225
	ds_bpermute_b32 v225, v186, v224
	s_waitcnt vmcnt(18)
	v_pk_fma_f32 v[20:21], v[20:21], v[60:61], v[236:237]
	v_pk_fma_f32 v[22:23], v[22:23], v[62:63], v[238:239]
	s_add_u32 s22, s88, 0xa0000
	s_addc_u32 s23, s89, 0
	global_store_dwordx4 v182, v[20:23], s[22:23] offset:512
	v_pk_mul_f32 v[144:145], v[20:21], v[20:21]
	v_pk_mul_f32 v[146:147], v[22:23], v[22:23]
	v_pk_mul_f32 v[220:221], v[168:169], v[20:21]
	v_pk_mul_f32 v[222:223], v[170:171], v[22:23]
	v_add_f32_e32 v144, v144, v145
	v_add_f32_e32 v146, v146, v147
	v_cvt_pk_bf16_f32 v194, v220, v221
	v_cvt_pk_bf16_f32 v195, v222, v223
	v_add_f32_e32 v144, v144, v146
	v_add_f32_e32 v187, v187, v144
	s_waitcnt lgkmcnt(0)
	v_add_f32_e32 v225, v224, v225
	s_and_saveexec_b64 vcc, s[4:5]
	global_atomic_add_f32 v184, v225, s[8:9] offset:576
	s_mov_b64 exec, vcc
	s_waitcnt vmcnt(17)
	v_pk_fma_f32 v[16:17], v[16:17], v[56:57], v[240:241]
	v_pk_fma_f32 v[18:19], v[18:19], v[58:59], v[242:243]
	s_add_u32 s22, s88, 0xa0000
	s_addc_u32 s23, s89, 0
	global_store_dwordx4 v182, v[16:19], s[22:23] offset:528
	v_pk_mul_f32 v[144:145], v[16:17], v[16:17]
	v_pk_mul_f32 v[146:147], v[18:19], v[18:19]
	v_pk_mul_f32 v[220:221], v[164:165], v[16:17]
	v_pk_mul_f32 v[222:223], v[166:167], v[18:19]
	v_add_f32_e32 v144, v144, v145
	v_add_f32_e32 v146, v146, v147
	v_cvt_pk_bf16_f32 v196, v220, v221
	v_cvt_pk_bf16_f32 v197, v222, v223
	v_add_f32_e32 v144, v144, v146
	v_add_f32_e32 v187, v187, v144
	s_add_u32 s22, s54, 0x50000
	s_addc_u32 s23, s55, 0
	global_store_dwordx4 v183, v[194:197], s[22:23] offset:256
	ds_bpermute_b32 v225, v185, v187
	s_waitcnt vmcnt(16)
	v_pk_fma_f32 v[12:13], v[12:13], v[76:77], v[244:245]
	v_pk_fma_f32 v[14:15], v[14:15], v[78:79], v[246:247]
	s_add_u32 s22, s88, 0xb0000
	s_addc_u32 s23, s89, 0
	global_store_dwordx4 v182, v[12:15], s[22:23]
	v_pk_mul_f32 v[144:145], v[12:13], v[12:13]
	v_pk_mul_f32 v[146:147], v[14:15], v[14:15]
	v_pk_mul_f32 v[220:221], v[176:177], v[12:13]
	v_pk_mul_f32 v[222:223], v[178:179], v[14:15]
	v_add_f32_e32 v144, v144, v145
	v_add_f32_e32 v146, v146, v147
	v_cvt_pk_bf16_f32 v216, v220, v221
	v_cvt_pk_bf16_f32 v217, v222, v223
	v_add_f32_e32 v224, v144, v146
	s_waitcnt vmcnt(15)
	v_pk_fma_f32 v[8:9], v[8:9], v[68:69], v[248:249]
	v_pk_fma_f32 v[10:11], v[10:11], v[70:71], v[250:251]
	s_add_u32 s22, s88, 0xb0000
	s_addc_u32 s23, s89, 0
	global_store_dwordx4 v182, v[8:11], s[22:23] offset:16
	v_pk_mul_f32 v[144:145], v[8:9], v[8:9]
	v_pk_mul_f32 v[146:147], v[10:11], v[10:11]
	v_pk_mul_f32 v[220:221], v[172:173], v[8:9]
	v_pk_mul_f32 v[222:223], v[174:175], v[10:11]
	v_add_f32_e32 v144, v144, v145
	v_add_f32_e32 v146, v146, v147
	v_cvt_pk_bf16_f32 v218, v220, v221
	v_cvt_pk_bf16_f32 v219, v222, v223
	v_add_f32_e32 v144, v144, v146
	v_add_f32_e32 v224, v224, v144
	s_add_u32 s22, s54, 0x58000
	s_addc_u32 s23, s55, 0
	global_store_dwordx4 v183, v[216:219], s[22:23]
	s_waitcnt lgkmcnt(0)
	v_add_f32_e32 v187, v187, v225
	ds_bpermute_b32 v225, v186, v187
	s_waitcnt vmcnt(14)
	v_pk_fma_f32 v[4:5], v[4:5], v[60:61], v[208:209]
	v_pk_fma_f32 v[6:7], v[6:7], v[62:63], v[210:211]
	s_add_u32 s22, s88, 0xb0000
	s_addc_u32 s23, s89, 0
	global_store_dwordx4 v182, v[4:7], s[22:23] offset:512
	v_pk_mul_f32 v[144:145], v[4:5], v[4:5]
	v_pk_mul_f32 v[146:147], v[6:7], v[6:7]
	v_pk_mul_f32 v[220:221], v[168:169], v[4:5]
	v_pk_mul_f32 v[222:223], v[170:171], v[6:7]
	v_add_f32_e32 v144, v144, v145
	v_add_f32_e32 v146, v146, v147
	v_cvt_pk_bf16_f32 v194, v220, v221
	v_cvt_pk_bf16_f32 v195, v222, v223
	v_add_f32_e32 v144, v144, v146
	v_add_f32_e32 v224, v224, v144
	s_waitcnt lgkmcnt(0)
	v_add_f32_e32 v225, v187, v225
	s_and_saveexec_b64 vcc, s[4:5]
	global_atomic_add_f32 v184, v225, s[8:9] offset:640
	s_mov_b64 exec, vcc
	s_waitcnt vmcnt(13)
	v_pk_fma_f32 v[0:1], v[0:1], v[56:57], v[212:213]
	v_pk_fma_f32 v[2:3], v[2:3], v[58:59], v[214:215]
	s_add_u32 s22, s88, 0xb0000
	s_addc_u32 s23, s89, 0
	global_store_dwordx4 v182, v[0:3], s[22:23] offset:528
	v_pk_mul_f32 v[144:145], v[0:1], v[0:1]
	v_pk_mul_f32 v[146:147], v[2:3], v[2:3]
	v_pk_mul_f32 v[220:221], v[164:165], v[0:1]
	v_pk_mul_f32 v[222:223], v[166:167], v[2:3]
	v_add_f32_e32 v144, v144, v145
	v_add_f32_e32 v146, v146, v147
	v_cvt_pk_bf16_f32 v196, v220, v221
	v_cvt_pk_bf16_f32 v197, v222, v223
	v_add_f32_e32 v144, v144, v146
	v_add_f32_e32 v224, v224, v144
	s_add_u32 s22, s54, 0x58000
	s_addc_u32 s23, s55, 0
	global_store_dwordx4 v183, v[194:197], s[22:23] offset:256
	ds_bpermute_b32 v225, v185, v224
	s_waitcnt lgkmcnt(0)
	v_add_f32_e32 v224, v224, v225
	ds_bpermute_b32 v225, v186, v224
	s_waitcnt lgkmcnt(0)
	v_add_f32_e32 v225, v224, v225
	s_and_saveexec_b64 vcc, s[4:5]
	global_atomic_add_f32 v184, v225, s[8:9] offset:704
	s_mov_b64 exec, vcc
	s_branch .LBB0_1346
;     __device__ __forceinline__ void operator()(const f32x4 (&acc)[2][2][4][2], const Unit& u, int wr_, int wc_, int fr_, int fq_) const {
;     ...
;         const int b = u.pm >> 5;
;         const int col0 = u.pn * BM + wc * 32 + 8 * fq;
;         const float* gp = gate + (size_t)b * 6144 + col0;
;         f32x4 gv[2][2], sv[2][2];
; #pragma unroll
;         for (int bj = 0; bj < 2; ++bj)
; #pragma unroll
;             for (int n = 0; n < 2; ++n) { gv[bj][n] = *(const f32x4*)(gp + bj * HALF + n * 4);
;                 sv[bj][n] = anext ? *(const f32x4*)(scale_next + (size_t)b * 6144 + col0 + bj * HALF + n * 4) + 1.0f : (f32x4){0.f, 0.f, 0.f, 0.f}; }
; #pragma unroll
;         for (int ai = 0; ai < 2; ++ai)
; #pragma unroll
;             for (int m = 0; m < 4; ++m) { int row = u.pm * BM + ai * HALF + wr * 64 + m * 16 + fr; asm volatile("" : "+v"(row));
;                 const size_t off = (size_t)row * 1024 + col0; float ss = 0.f;
; #pragma unroll
;                 for (int bj = 0; bj < 2; ++bj) { u32x4 w;
; #pragma unroll
;                     for (int n = 0; n < 2; ++n) { const f32x4 xi = *(const f32x4*)(xin + off + bj * HALF + n * 4);
;                         const f32x4 xn = xi + gv[bj][n] * acc[ai][bj][m][n];
;                         *(f32x4*)(xout + off + bj * HALF + n * 4) = xn;
.Lrg6_fastn:
	s_movk_i32 s49, 0x4000
	v_bfe_u32 v227, v190, 4, 2
	v_lshrrev_b32_e32 v144, 1, v190
	v_and_b32_e32 v144, 0x60, v144
	s_lshl_b32 s4, s41, 8
	v_lshlrev_b32_e32 v145, 3, v227
	v_or3_b32 v180, v144, s4, v145
	v_lshlrev_b32_e32 v181, 2, v180
	s_ashr_i32 s4, s33, 5
	s_mul_i32 s4, s4, 0x6000
	s_add_u32 s2, s24, s4
	s_addc_u32 s3, s25, 0
	global_load_dwordx4 v[76:79], v181, s[2:3]
	global_load_dwordx4 v[68:71], v181, s[2:3] offset:16
	global_load_dwordx4 v[60:63], v181, s[2:3] offset:512
	global_load_dwordx4 v[56:59], v181, s[2:3] offset:528
	s_lshl_b32 s4, s33, 8
	v_ashrrev_i32_e32 v144, 2, v190
	v_and_b32_e32 v144, 0xffffffc0, v144
	v_and_or_b32 v145, v190, 15, s4
	v_add_u32_e32 v184, v145, v144
	v_lshl_add_u32 v182, v184, 10, v180
	v_lshlrev_b32_e32 v182, 2, v182
	global_load_dwordx4 v[228:231], v182, s[88:89]
	global_load_dwordx4 v[232:235], v182, s[88:89] offset:16
	global_load_dwordx4 v[236:239], v182, s[88:89] offset:512
	global_load_dwordx4 v[240:243], v182, s[88:89] offset:528
	s_add_u32 s2, s88, 0x10000
	s_addc_u32 s3, s89, 0
	global_load_dwordx4 v[244:247], v182, s[2:3]
	s_add_u32 s2, s88, 0x10000
	s_addc_u32 s3, s89, 0
	global_load_dwordx4 v[248:251], v182, s[2:3] offset:16
	s_add_u32 s2, s88, 0x10000
	s_addc_u32 s3, s89, 0
	global_load_dwordx4 v[208:211], v182, s[2:3] offset:512
	s_add_u32 s2, s88, 0x10000
	s_addc_u32 s3, s89, 0
	global_load_dwordx4 v[212:215], v182, s[2:3] offset:528
	s_waitcnt vmcnt(8)
	s_waitcnt vmcnt(7)
	v_pk_fma_f32 v[64:65], v[64:65], v[76:77], v[228:229]
	v_pk_fma_f32 v[66:67], v[66:67], v[78:79], v[230:231]
	global_store_dwordx4 v182, v[64:67], s[88:89]
	s_add_u32 s2, s88, 0x20000
	s_addc_u32 s3, s89, 0
	global_load_dwordx4 v[228:231], v182, s[2:3]
	s_waitcnt vmcnt(8)
	v_pk_fma_f32 v[140:141], v[140:141], v[68:69], v[232:233]
	v_pk_fma_f32 v[142:143], v[142:143], v[70:71], v[234:235]
	global_store_dwordx4 v182, v[140:143], s[88:89] offset:16
	s_add_u32 s2, s88, 0x20000
	s_addc_u32 s3, s89, 0
	global_load_dwordx4 v[232:235], v182, s[2:3] offset:16
	s_waitcnt vmcnt(9)
	v_pk_fma_f32 v[136:137], v[136:137], v[60:61], v[236:237]
	v_pk_fma_f32 v[138:139], v[138:139], v[62:63], v[238:239]
	global_store_dwordx4 v182, v[136:139], s[88:89] offset:512
	s_add_u32 s2, s88, 0x20000
	s_addc_u32 s3, s89, 0
	global_load_dwordx4 v[236:239], v182, s[2:3] offset:512
	s_waitcnt vmcnt(10)
	v_pk_fma_f32 v[132:133], v[132:133], v[56:57], v[240:241]
	v_pk_fma_f32 v[134:135], v[134:135], v[58:59], v[242:243]
	global_store_dwordx4 v182, v[132:135], s[88:89] offset:528
	s_add_u32 s2, s88, 0x20000
	s_addc_u32 s3, s89, 0
	global_load_dwordx4 v[240:243], v182, s[2:3] offset:528
	s_waitcnt vmcnt(11)
	v_pk_fma_f32 v[128:129], v[128:129], v[76:77], v[244:245]
	v_pk_fma_f32 v[130:131], v[130:131], v[78:79], v[246:247]
	s_add_u32 s22, s88, 0x10000
	s_addc_u32 s23, s89, 0
	global_store_dwordx4 v182, v[128:131], s[22:23]
	s_add_u32 s2, s88, 0x30000
	s_addc_u32 s3, s89, 0
	global_load_dwordx4 v[244:247], v182, s[2:3]
	s_waitcnt vmcnt(12)
	v_pk_fma_f32 v[124:125], v[124:125], v[68:69], v[248:249]
	v_pk_fma_f32 v[126:127], v[126:127], v[70:71], v[250:251]
	s_add_u32 s22, s88, 0x10000
	s_addc_u32 s23, s89, 0
	global_store_dwordx4 v182, v[124:127], s[22:23] offset:16
	s_add_u32 s2, s88, 0x30000
	s_addc_u32 s3, s89, 0
	global_load_dwordx4 v[248:251], v182, s[2:3] offset:16
	s_waitcnt vmcnt(13)
	v_pk_fma_f32 v[120:121], v[120:121], v[60:61], v[208:209]
	v_pk_fma_f32 v[122:123], v[122:123], v[62:63], v[210:211]
	s_add_u32 s22, s88, 0x10000
	s_addc_u32 s23, s89, 0
	global_store_dwordx4 v182, v[120:123], s[22:23] offset:512
	s_add_u32 s2, s88, 0x30000
	s_addc_u32 s3, s89, 0
	global_load_dwordx4 v[208:211], v182, s[2:3] offset:512
	s_waitcnt vmcnt(14)
	v_pk_fma_f32 v[116:117], v[116:117], v[56:57], v[212:213]
	v_pk_fma_f32 v[118:119], v[118:119], v[58:59], v[214:215]
	s_add_u32 s22, s88, 0x10000
	s_addc_u32 s23, s89, 0
	global_store_dwordx4 v182, v[116:119], s[22:23] offset:528
	s_add_u32 s2, s88, 0x30000
	s_addc_u32 s3, s89, 0
	global_load_dwordx4 v[212:215], v182, s[2:3] offset:528
	s_waitcnt vmcnt(14)
	v_pk_fma_f32 v[112:113], v[112:113], v[76:77], v[228:229]
	v_pk_fma_f32 v[114:115], v[114:115], v[78:79], v[230:231]
	s_add_u32 s22, s88, 0x20000
	s_addc_u32 s23, s89, 0
	global_store_dwordx4 v182, v[112:115], s[22:23]
	s_add_u32 s2, s88, 0x80000
	s_addc_u32 s3, s89, 0
	global_load_dwordx4 v[228:231], v182, s[2:3]
	s_waitcnt vmcnt(14)
	v_pk_fma_f32 v[108:109], v[108:109], v[68:69], v[232:233]
	v_pk_fma_f32 v[110:111], v[110:111], v[70:71], v[234:235]
	s_add_u32 s22, s88, 0x20000
	s_addc_u32 s23, s89, 0
	global_store_dwordx4 v182, v[108:111], s[22:23] offset:16
	s_add_u32 s2, s88, 0x80000
	s_addc_u32 s3, s89, 0
	global_load_dwordx4 v[232:235], v182, s[2:3] offset:16
	s_waitcnt vmcnt(14)
	v_pk_fma_f32 v[104:105], v[104:105], v[60:61], v[236:237]
	v_pk_fma_f32 v[106:107], v[106:107], v[62:63], v[238:239]
	s_add_u32 s22, s88, 0x20000
	s_addc_u32 s23, s89, 0
	global_store_dwordx4 v182, v[104:107], s[22:23] offset:512
	s_add_u32 s2, s88, 0x80000
	s_addc_u32 s3, s89, 0
	global_load_dwordx4 v[236:239], v182, s[2:3] offset:512
	s_waitcnt vmcnt(14)
	v_pk_fma_f32 v[100:101], v[100:101], v[56:57], v[240:241]
	v_pk_fma_f32 v[102:103], v[102:103], v[58:59], v[242:243]
	s_add_u32 s22, s88, 0x20000
	s_addc_u32 s23, s89, 0
	global_store_dwordx4 v182, v[100:103], s[22:23] offset:528
	s_add_u32 s2, s88, 0x80000
	s_addc_u32 s3, s89, 0
	global_load_dwordx4 v[240:243], v182, s[2:3] offset:528
	s_waitcnt vmcnt(14)
;     __device__ __forceinline__ void operator()(const f32x4 (&acc)[2][2][4][2], const Unit& u, int wr_, int wc_, int fr_, int fq_) const {
;     ...
;         const int b = u.pm >> 5;
;         const int col0 = u.pn * BM + wc * 32 + 8 * fq;
;         const float* gp = gate + (size_t)b * 6144 + col0;
;         f32x4 gv[2][2], sv[2][2];
; #pragma unroll
;         for (int bj = 0; bj < 2; ++bj)
; #pragma unroll
;             for (int n = 0; n < 2; ++n) { gv[bj][n] = *(const f32x4*)(gp + bj * HALF + n * 4);
;                 sv[bj][n] = anext ? *(const f32x4*)(scale_next + (size_t)b * 6144 + col0 + bj * HALF + n * 4) + 1.0f : (f32x4){0.f, 0.f, 0.f, 0.f}; }
; #pragma unroll
;         for (int ai = 0; ai < 2; ++ai)
; #pragma unroll
;             for (int m = 0; m < 4; ++m) { int row = u.pm * BM + ai * HALF + wr * 64 + m * 16 + fr; asm volatile("" : "+v"(row));
;                 const size_t off = (size_t)row * 1024 + col0; float ss = 0.f;
; #pragma unroll
;                 for (int bj = 0; bj < 2; ++bj) { u32x4 w;
; #pragma unroll
;                     for (int n = 0; n < 2; ++n) { const f32x4 xi = *(const f32x4*)(xin + off + bj * HALF + n * 4);
;                         const f32x4 xn = xi + gv[bj][n] * acc[ai][bj][m][n];
;                         *(f32x4*)(xout + off + bj * HALF + n * 4) = xn;
	v_pk_fma_f32 v[96:97], v[96:97], v[76:77], v[244:245]
	v_pk_fma_f32 v[98:99], v[98:99], v[78:79], v[246:247]
	s_add_u32 s22, s88, 0x30000
	s_addc_u32 s23, s89, 0
	global_store_dwordx4 v182, v[96:99], s[22:23]
	s_add_u32 s2, s88, 0x90000
	s_addc_u32 s3, s89, 0
	global_load_dwordx4 v[244:247], v182, s[2:3]
	s_waitcnt vmcnt(14)
	v_pk_fma_f32 v[92:93], v[92:93], v[68:69], v[248:249]
	v_pk_fma_f32 v[94:95], v[94:95], v[70:71], v[250:251]
	s_add_u32 s22, s88, 0x30000
	s_addc_u32 s23, s89, 0
	global_store_dwordx4 v182, v[92:95], s[22:23] offset:16
	s_add_u32 s2, s88, 0x90000
	s_addc_u32 s3, s89, 0
	global_load_dwordx4 v[248:251], v182, s[2:3] offset:16
	s_waitcnt vmcnt(14)
	v_pk_fma_f32 v[88:89], v[88:89], v[60:61], v[208:209]
	v_pk_fma_f32 v[90:91], v[90:91], v[62:63], v[210:211]
	s_add_u32 s22, s88, 0x30000
	s_addc_u32 s23, s89, 0
	global_store_dwordx4 v182, v[88:91], s[22:23] offset:512
	s_add_u32 s2, s88, 0x90000
	s_addc_u32 s3, s89, 0
	global_load_dwordx4 v[208:211], v182, s[2:3] offset:512
	s_waitcnt vmcnt(14)
	v_pk_fma_f32 v[84:85], v[84:85], v[56:57], v[212:213]
	v_pk_fma_f32 v[86:87], v[86:87], v[58:59], v[214:215]
	s_add_u32 s22, s88, 0x30000
	s_addc_u32 s23, s89, 0
	global_store_dwordx4 v182, v[84:87], s[22:23] offset:528
	s_add_u32 s2, s88, 0x90000
	s_addc_u32 s3, s89, 0
	global_load_dwordx4 v[212:215], v182, s[2:3] offset:528
	s_waitcnt vmcnt(14)
	v_pk_fma_f32 v[80:81], v[80:81], v[76:77], v[228:229]
	v_pk_fma_f32 v[82:83], v[82:83], v[78:79], v[230:231]
	s_add_u32 s22, s88, 0x80000
	s_addc_u32 s23, s89, 0
	global_store_dwordx4 v182, v[80:83], s[22:23]
	s_add_u32 s2, s88, 0xa0000
	s_addc_u32 s3, s89, 0
	global_load_dwordx4 v[228:231], v182, s[2:3]
	s_waitcnt vmcnt(14)
	v_pk_fma_f32 v[72:73], v[72:73], v[68:69], v[232:233]
	v_pk_fma_f32 v[74:75], v[74:75], v[70:71], v[234:235]
	s_add_u32 s22, s88, 0x80000
	s_addc_u32 s23, s89, 0
	global_store_dwordx4 v182, v[72:75], s[22:23] offset:16
	s_add_u32 s2, s88, 0xa0000
	s_addc_u32 s3, s89, 0
	global_load_dwordx4 v[232:235], v182, s[2:3] offset:16
	s_waitcnt vmcnt(14)
	v_pk_fma_f32 v[52:53], v[52:53], v[60:61], v[236:237]
	v_pk_fma_f32 v[54:55], v[54:55], v[62:63], v[238:239]
	s_add_u32 s22, s88, 0x80000
	s_addc_u32 s23, s89, 0
	global_store_dwordx4 v182, v[52:55], s[22:23] offset:512
	s_add_u32 s2, s88, 0xa0000
	s_addc_u32 s3, s89, 0
	global_load_dwordx4 v[236:239], v182, s[2:3] offset:512
	s_waitcnt vmcnt(14)
	v_pk_fma_f32 v[48:49], v[48:49], v[56:57], v[240:241]
	v_pk_fma_f32 v[50:51], v[50:51], v[58:59], v[242:243]
	s_add_u32 s22, s88, 0x80000
	s_addc_u32 s23, s89, 0
	global_store_dwordx4 v182, v[48:51], s[22:23] offset:528
	s_add_u32 s2, s88, 0xa0000
	s_addc_u32 s3, s89, 0
	global_load_dwordx4 v[240:243], v182, s[2:3] offset:528
	s_waitcnt vmcnt(14)
	v_pk_fma_f32 v[44:45], v[44:45], v[76:77], v[244:245]
	v_pk_fma_f32 v[46:47], v[46:47], v[78:79], v[246:247]
	s_add_u32 s22, s88, 0x90000
	s_addc_u32 s23, s89, 0
	global_store_dwordx4 v182, v[44:47], s[22:23]
	s_add_u32 s2, s88, 0xb0000
	s_addc_u32 s3, s89, 0
	global_load_dwordx4 v[244:247], v182, s[2:3]
	s_waitcnt vmcnt(14)
	v_pk_fma_f32 v[40:41], v[40:41], v[68:69], v[248:249]
	v_pk_fma_f32 v[42:43], v[42:43], v[70:71], v[250:251]
	s_add_u32 s22, s88, 0x90000
	s_addc_u32 s23, s89, 0
	global_store_dwordx4 v182, v[40:43], s[22:23] offset:16
	s_add_u32 s2, s88, 0xb0000
	s_addc_u32 s3, s89, 0
	global_load_dwordx4 v[248:251], v182, s[2:3] offset:16
	s_waitcnt vmcnt(14)
	v_pk_fma_f32 v[36:37], v[36:37], v[60:61], v[208:209]
	v_pk_fma_f32 v[38:39], v[38:39], v[62:63], v[210:211]
	s_add_u32 s22, s88, 0x90000
	s_addc_u32 s23, s89, 0
	global_store_dwordx4 v182, v[36:39], s[22:23] offset:512
	s_add_u32 s2, s88, 0xb0000
	s_addc_u32 s3, s89, 0
	global_load_dwordx4 v[208:211], v182, s[2:3] offset:512
	s_waitcnt vmcnt(14)
	v_pk_fma_f32 v[32:33], v[32:33], v[56:57], v[212:213]
	v_pk_fma_f32 v[34:35], v[34:35], v[58:59], v[214:215]
	s_add_u32 s22, s88, 0x90000
	s_addc_u32 s23, s89, 0
	global_store_dwordx4 v182, v[32:35], s[22:23] offset:528
	s_add_u32 s2, s88, 0xb0000
	s_addc_u32 s3, s89, 0
	global_load_dwordx4 v[212:215], v182, s[2:3] offset:528
	s_waitcnt vmcnt(14)
	v_pk_fma_f32 v[28:29], v[28:29], v[76:77], v[228:229]
	v_pk_fma_f32 v[30:31], v[30:31], v[78:79], v[230:231]
	s_add_u32 s22, s88, 0xa0000
	s_addc_u32 s23, s89, 0
	global_store_dwordx4 v182, v[28:31], s[22:23]
	s_waitcnt vmcnt(13)
	v_pk_fma_f32 v[24:25], v[24:25], v[68:69], v[232:233]
	v_pk_fma_f32 v[26:27], v[26:27], v[70:71], v[234:235]
	s_add_u32 s22, s88, 0xa0000
	s_addc_u32 s23, s89, 0
	global_store_dwordx4 v182, v[24:27], s[22:23] offset:16
	s_waitcnt vmcnt(12)
	v_pk_fma_f32 v[20:21], v[20:21], v[60:61], v[236:237]
	v_pk_fma_f32 v[22:23], v[22:23], v[62:63], v[238:239]
	s_add_u32 s22, s88, 0xa0000
	s_addc_u32 s23, s89, 0
	global_store_dwordx4 v182, v[20:23], s[22:23] offset:512
	s_waitcnt vmcnt(11)
	v_pk_fma_f32 v[16:17], v[16:17], v[56:57], v[240:241]
	v_pk_fma_f32 v[18:19], v[18:19], v[58:59], v[242:243]
	s_add_u32 s22, s88, 0xa0000
	s_addc_u32 s23, s89, 0
	global_store_dwordx4 v182, v[16:19], s[22:23] offset:528
	s_waitcnt vmcnt(10)
	v_pk_fma_f32 v[12:13], v[12:13], v[76:77], v[244:245]
	v_pk_fma_f32 v[14:15], v[14:15], v[78:79], v[246:247]
	s_add_u32 s22, s88, 0xb0000
	s_addc_u32 s23, s89, 0
	global_store_dwordx4 v182, v[12:15], s[22:23]
	s_waitcnt vmcnt(9)
	v_pk_fma_f32 v[8:9], v[8:9], v[68:69], v[248:249]
	v_pk_fma_f32 v[10:11], v[10:11], v[70:71], v[250:251]
	s_add_u32 s22, s88, 0xb0000
	s_addc_u32 s23, s89, 0
	global_store_dwordx4 v182, v[8:11], s[22:23] offset:16
	s_waitcnt vmcnt(8)
	v_pk_fma_f32 v[4:5], v[4:5], v[60:61], v[208:209]
	v_pk_fma_f32 v[6:7], v[6:7], v[62:63], v[210:211]
	s_add_u32 s22, s88, 0xb0000
	s_addc_u32 s23, s89, 0
	global_store_dwordx4 v182, v[4:7], s[22:23] offset:512
	s_waitcnt vmcnt(7)
	v_pk_fma_f32 v[0:1], v[0:1], v[56:57], v[212:213]
	v_pk_fma_f32 v[2:3], v[2:3], v[58:59], v[214:215]
	s_add_u32 s22, s88, 0xb0000
	s_addc_u32 s23, s89, 0
	global_store_dwordx4 v182, v[0:3], s[22:23] offset:528
	s_branch .LBB0_1346
